# g2 main-loop restructure applied to all nine 256x128 GEMM loops (P2,P3,P4,P9) on top of row-phase load hoisting, attention K/V prefetch
# baseline (speedup 1.0000x reference)
; DEVI int opaque_tid() { int t = (int)threadIdx.x; asm volatile("" : "+v"(t)); return t; }
; DEVI void g2_issue(const G2Tile& t, int kt, int st, char* smem) {
;     const int tid = opaque_tid(), lane = tid & 63, w = tid >> 6;
;     const int rr = lane >> 2, sch = (lane & 3) ^ ((lane >> 5) << 1);
;     const bf16_t* ap = t.A + (size_t)kt * 32 + (size_t)(w * 16 + rr) * t.lda + sch * 8;
;     const bf16_t* bp = t.Bt + (size_t)kt * 32 + (size_t)(w * 16 + rr) * t.ldb + sch * 8;
;     char* sa = smem + st * 24576 + w * 1024 + lane * 16;
; #pragma unroll
;     for (int i = 0; i < 4; ++i) __builtin_amdgcn_global_load_lds((const unsigned*)(ap + (size_t)(64 * i) * t.lda), (unsigned*)(sa + i * 4096), 16, 0, 0);
; #pragma unroll
;     for (int i = 0; i < 2; ++i) __builtin_amdgcn_global_load_lds((const unsigned*)(bp + (size_t)(64 * i) * t.ldb), (unsigned*)(sa + 16384 + i * 4096), 16, 0, 0);
; }
; DEVI void g2_prologue(const G2Tile& t, int st, char* smem) {
;     g2_issue(t, 0, st, smem);
;     g2_issue(t, 1, st == 2 ? 0 : st + 1, smem);
; }
; template <bool TRANS, class Epi>
; DEVI int g2_body(const G2Tile& t, int st, char* smem, bool has_next, const G2Tile& nxt, const Epi& epi) {
;     const int tid = opaque_tid(), lane = tid & 63, w = tid >> 6, wr = w >> 1, wc = w & 1, fr = lane & 15, fq = lane >> 4;
;     f32x4 acc[8][4];
; #pragma unroll
;     for (int m = 0; m < 8; ++m)
; #pragma unroll
;         for (int n = 0; n < 4; ++n) acc[m][n] = (f32x4){0.f, 0.f, 0.f, 0.f};
;     const int frag = fr * 64 + ((fq ^ ((fr >> 3) << 1)) << 4);
;     const int nk = t.nk;
.LBB0_476:
	v_mov_b32_e32 v133, v172
	s_mov_b64 s[50:51], 0
	v_lshrrev_b32_e32 v1, 2, v133
	v_lshrrev_b32_e32 v130, 4, v133
	v_and_b32_e32 v1, 2, v1
	v_and_b32_e32 v134, 15, v133
	v_bitop3_b32 v1, v130, v1, 3 bitop3:0x6c
	v_lshlrev_b32_e32 v0, 6, v134
	v_lshlrev_b32_e32 v1, 4, v1
	v_add3_u32 v135, 0, v0, v1
	v_lshlrev_b32_e32 v0, 6, v133
	v_bfe_u32 v132, v133, 6, 1
	v_and_b32_e32 v136, 0xffffe000, v0
	v_mov_b32_e32 v0, 0
	v_bfe_u32 v131, v133, 4, 2
	v_lshlrev_b32_e32 v128, 12, v132
	v_mov_b32_e32 v1, v0
	v_mov_b32_e32 v2, v0
	v_mov_b32_e32 v3, v0
	v_mov_b32_e32 v4, v0
	v_mov_b32_e32 v5, v0
	v_mov_b32_e32 v6, v0
	v_mov_b32_e32 v7, v0
	v_mov_b32_e32 v8, v0
	v_mov_b32_e32 v9, v0
	v_mov_b32_e32 v10, v0
	v_mov_b32_e32 v11, v0
	v_mov_b32_e32 v12, v0
	v_mov_b32_e32 v13, v0
	v_mov_b32_e32 v14, v0
	v_mov_b32_e32 v15, v0
	v_mov_b32_e32 v16, v0
	v_mov_b32_e32 v17, v0
	v_mov_b32_e32 v18, v0
	v_mov_b32_e32 v19, v0
	v_mov_b32_e32 v20, v0
	v_mov_b32_e32 v21, v0
	v_mov_b32_e32 v22, v0
	v_mov_b32_e32 v23, v0
	v_mov_b32_e32 v24, v0
	v_mov_b32_e32 v25, v0
	v_mov_b32_e32 v26, v0
	v_mov_b32_e32 v27, v0
	v_mov_b32_e32 v28, v0
	v_mov_b32_e32 v29, v0
	v_mov_b32_e32 v30, v0
	v_mov_b32_e32 v31, v0
	v_mov_b32_e32 v32, v0
	v_mov_b32_e32 v33, v0
	v_mov_b32_e32 v34, v0
	v_mov_b32_e32 v35, v0
	v_mov_b32_e32 v36, v0
	v_mov_b32_e32 v37, v0
	v_mov_b32_e32 v38, v0
	v_mov_b32_e32 v39, v0
	v_mov_b32_e32 v40, v0
	v_mov_b32_e32 v41, v0
	v_mov_b32_e32 v42, v0
	v_mov_b32_e32 v43, v0
	v_mov_b32_e32 v44, v0
	v_mov_b32_e32 v45, v0
	v_mov_b32_e32 v46, v0
	v_mov_b32_e32 v47, v0
	v_mov_b32_e32 v48, v0
	v_mov_b32_e32 v49, v0
	v_mov_b32_e32 v50, v0
	v_mov_b32_e32 v51, v0
	v_mov_b32_e32 v52, v0
	v_mov_b32_e32 v53, v0
	v_mov_b32_e32 v54, v0
	v_mov_b32_e32 v55, v0
	v_mov_b32_e32 v56, v0
	v_mov_b32_e32 v57, v0
	v_mov_b32_e32 v58, v0
	v_mov_b32_e32 v59, v0
	v_mov_b32_e32 v60, v0
	v_mov_b32_e32 v61, v0
	v_mov_b32_e32 v62, v0
	v_mov_b32_e32 v63, v0
	v_mov_b32_e32 v64, v0
	v_mov_b32_e32 v65, v0
	v_mov_b32_e32 v66, v0
	v_mov_b32_e32 v67, v0
	v_mov_b32_e32 v68, v0
	v_mov_b32_e32 v69, v0
	v_mov_b32_e32 v70, v0
	v_mov_b32_e32 v71, v0
	v_mov_b32_e32 v72, v0
	v_mov_b32_e32 v73, v0
	v_mov_b32_e32 v74, v0
	v_mov_b32_e32 v75, v0
	v_mov_b32_e32 v76, v0
	v_mov_b32_e32 v77, v0
	v_mov_b32_e32 v78, v0
	v_mov_b32_e32 v79, v0
	v_mov_b32_e32 v80, v0
	v_mov_b32_e32 v81, v0
	v_mov_b32_e32 v82, v0
	v_mov_b32_e32 v83, v0
	v_mov_b32_e32 v84, v0
	v_mov_b32_e32 v85, v0
	v_mov_b32_e32 v86, v0
	v_mov_b32_e32 v87, v0
	v_mov_b32_e32 v96, v0
	v_mov_b32_e32 v97, v0
	v_mov_b32_e32 v98, v0
	v_mov_b32_e32 v99, v0
	v_mov_b32_e32 v108, v0
	v_mov_b32_e32 v109, v0
	v_mov_b32_e32 v110, v0
	v_mov_b32_e32 v111, v0
	v_mov_b32_e32 v112, v0
	v_mov_b32_e32 v113, v0
	v_mov_b32_e32 v114, v0
	v_mov_b32_e32 v115, v0
	v_mov_b32_e32 v116, v0
	v_mov_b32_e32 v117, v0
	v_mov_b32_e32 v118, v0
	v_mov_b32_e32 v119, v0
	v_mov_b32_e32 v120, v0
	v_mov_b32_e32 v121, v0
	v_mov_b32_e32 v122, v0
	v_mov_b32_e32 v123, v0
	v_mov_b32_e32 v124, v0
	v_mov_b32_e32 v125, v0
	v_mov_b32_e32 v126, v0
	v_mov_b32_e32 v127, v0
	v_mov_b32_e32 v88, v0
	v_mov_b32_e32 v89, v0
	v_mov_b32_e32 v90, v0
	v_mov_b32_e32 v91, v0
	v_mov_b32_e32 v92, v0
	v_mov_b32_e32 v93, v0
	v_mov_b32_e32 v94, v0
	v_mov_b32_e32 v95, v0
	v_mov_b32_e32 v100, v0
	v_mov_b32_e32 v101, v0
	v_mov_b32_e32 v102, v0
	v_mov_b32_e32 v103, v0
	v_mov_b32_e32 v104, v0
	v_mov_b32_e32 v105, v0
	v_mov_b32_e32 v106, v0
	v_mov_b32_e32 v107, v0
	v_and_b32_e32 v224, 3, v172
	v_lshrrev_b32_e32 v225, 4, v172
	v_bitop3_b32 v224, v225, v224, 2 bitop3:0x6c
	v_ashrrev_i32_e32 v225, 6, v172
	v_bfe_u32 v222, v172, 2, 4
	v_readfirstlane_b32 s32, v225
	v_lshl_or_b32 v222, v225, 4, v222
	v_lshlrev_b32_e32 v222, 11, v222
	v_lshl_or_b32 v222, v224, 4, v222
	v_mov_b32_e32 v223, 0
	s_lshl_b32 s32, s32, 10
	v_lshl_add_u64 v[208:209], s[34:35], 0, v[222:223]
	v_lshl_add_u64 v[208:209], v[208:209], 0, s[12:13]
	v_lshl_add_u64 v[210:211], s[34:35], 0, v[222:223]
	v_lshl_add_u64 v[210:211], v[210:211], 0, s[14:15]
	v_lshl_add_u64 v[212:213], s[34:35], 0, v[222:223]
	s_mov_b64 s[98:99], 0x40080
	v_lshl_add_u64 v[212:213], v[212:213], 0, s[98:99]
	v_lshl_add_u64 v[214:215], s[34:35], 0, v[222:223]
	s_mov_b64 s[98:99], 0x60080
	v_lshl_add_u64 v[214:215], v[214:215], 0, s[98:99]
	v_lshl_add_u64 v[218:219], s[36:37], 0, v[222:223]
	v_lshl_add_u64 v[218:219], v[218:219], 0, s[12:13]
	v_lshl_add_u64 v[220:221], s[36:37], 0, v[222:223]
	v_lshl_add_u64 v[220:221], v[220:221], 0, s[14:15]
; template <bool TRANS, class Epi>
; DEVI int g2_body(const G2Tile& t, int st, char* smem, bool has_next, const G2Tile& nxt, const Epi& epi) {
;     ...
;     for (int kt = 0; kt < nk; ++kt) {
;         if (kt + 1 < nk) asm volatile("s_waitcnt vmcnt(6)" ::: "memory");
;         else asm volatile("s_waitcnt vmcnt(0)" ::: "memory");
;         __syncthreads();
;         if (kt + 2 < nk) g2_issue(t, kt + 2, st >= 1 ? st - 1 : 2, smem);
;         const char* sa = smem + st * 24576 + frag;
;         bf16x8 bfr[4];
; #pragma unroll
;         for (int n = 0; n < 4; ++n) bfr[n] = *(const bf16x8*)(sa + (16 + wc * 4 + n) * 1024);
; #pragma unroll
;         for (int mh = 0; mh < 2; ++mh) {
;             bf16x8 af[4];
; #pragma unroll
;             for (int m = 0; m < 4; ++m) af[m] = *(const bf16x8*)(sa + (wr * 8 + mh * 4 + m) * 1024);
;             __builtin_amdgcn_s_setprio(1);
; #pragma unroll
;             for (int m = 0; m < 4; ++m)
; #pragma unroll
;                 for (int n = 0; n < 4; ++n)
;                     acc[mh * 4 + m][n] = TRANS ? __builtin_amdgcn_mfma_f32_16x16x32_bf16(bfr[n], af[m], acc[mh * 4 + m][n], 0, 0, 0)
;                                                : __builtin_amdgcn_mfma_f32_16x16x32_bf16(af[m], bfr[n], acc[mh * 4 + m][n], 0, 0, 0);
;             __builtin_amdgcn_s_setprio(0);
;         }
;         st = st == 2 ? 0 : st + 1;
;     }
.LBB0_477:
	s_waitcnt vmcnt(6)
	s_waitcnt lgkmcnt(0)
	s_barrier
	s_mul_i32 s18, s60, 0x6000
	s_add_i32 s16, s18, 0xffffa000
	s_cmp_gt_i32 s60, 0
	s_cselect_b32 s16, s16, 0xc000
	s_add_i32 s16, s16, s32
	v_add_u32_e32 v137, s18, v135
	v_add_u32_e32 v150, v137, v128
	v_add_u32_e32 v137, v137, v136
	ds_read_b128 v[138:141], v150 offset:16384
	ds_read_b128 v[142:145], v150 offset:17408
	ds_read_b128 v[146:149], v150 offset:18432
	ds_read_b128 v[150:153], v150 offset:19456
	ds_read_b128 v[154:157], v137
	ds_read_b128 v[158:161], v137 offset:1024
	ds_read_b128 v[162:165], v137 offset:2048
	ds_read_b128 v[166:169], v137 offset:3072
	ds_read_b128 v[192:195], v137 offset:4096
	ds_read_b128 v[196:199], v137 offset:5120
	ds_read_b128 v[200:203], v137 offset:6144
	ds_read_b128 v[204:207], v137 offset:7168
	s_mov_b32 m0, s16
	s_nop 0
	global_load_lds_dwordx4 v[208:209], off
	v_lshl_add_u64 v[208:209], v[208:209], 0, 64
	s_add_i32 m0, s16, 0x1000
	s_setprio 1
	s_waitcnt lgkmcnt(7)
	v_mfma_f32_16x16x32_bf16 v[124:127], v[154:157], v[138:141], v[124:127]
	v_mfma_f32_16x16x32_bf16 v[120:123], v[154:157], v[142:145], v[120:123]
	v_mfma_f32_16x16x32_bf16 v[116:119], v[154:157], v[146:149], v[116:119]
	v_mfma_f32_16x16x32_bf16 v[112:115], v[154:157], v[150:153], v[112:115]
	global_load_lds_dwordx4 v[210:211], off
	v_lshl_add_u64 v[210:211], v[210:211], 0, 64
	s_add_i32 m0, s16, 0x2000
	s_waitcnt lgkmcnt(6)
	v_mfma_f32_16x16x32_bf16 v[108:111], v[158:161], v[138:141], v[108:111]
	v_mfma_f32_16x16x32_bf16 v[96:99], v[158:161], v[142:145], v[96:99]
	v_mfma_f32_16x16x32_bf16 v[84:87], v[158:161], v[146:149], v[84:87]
	v_mfma_f32_16x16x32_bf16 v[80:83], v[158:161], v[150:153], v[80:83]
	global_load_lds_dwordx4 v[212:213], off
	v_lshl_add_u64 v[212:213], v[212:213], 0, 64
	s_add_i32 m0, s16, 0x3000
	s_waitcnt lgkmcnt(5)
	v_mfma_f32_16x16x32_bf16 v[76:79], v[162:165], v[138:141], v[76:79]
	v_mfma_f32_16x16x32_bf16 v[72:75], v[162:165], v[142:145], v[72:75]
	v_mfma_f32_16x16x32_bf16 v[68:71], v[162:165], v[146:149], v[68:71]
	v_mfma_f32_16x16x32_bf16 v[64:67], v[162:165], v[150:153], v[64:67]
	global_load_lds_dwordx4 v[214:215], off
	v_lshl_add_u64 v[214:215], v[214:215], 0, 64
	s_add_i32 m0, s16, 0x4000
	s_waitcnt lgkmcnt(4)
	v_mfma_f32_16x16x32_bf16 v[60:63], v[166:169], v[138:141], v[60:63]
	v_mfma_f32_16x16x32_bf16 v[56:59], v[166:169], v[142:145], v[56:59]
	v_mfma_f32_16x16x32_bf16 v[52:55], v[166:169], v[146:149], v[52:55]
	v_mfma_f32_16x16x32_bf16 v[48:51], v[166:169], v[150:153], v[48:51]
	global_load_lds_dwordx4 v[218:219], off
	v_lshl_add_u64 v[218:219], v[218:219], 0, 64
	s_add_i32 m0, s16, 0x5000
	s_waitcnt lgkmcnt(3)
	v_mfma_f32_16x16x32_bf16 v[44:47], v[192:195], v[138:141], v[44:47]
	v_mfma_f32_16x16x32_bf16 v[40:43], v[192:195], v[142:145], v[40:43]
	v_mfma_f32_16x16x32_bf16 v[36:39], v[192:195], v[146:149], v[36:39]
	v_mfma_f32_16x16x32_bf16 v[32:35], v[192:195], v[150:153], v[32:35]
	global_load_lds_dwordx4 v[220:221], off
	v_lshl_add_u64 v[220:221], v[220:221], 0, 64
	s_waitcnt lgkmcnt(2)
	v_mfma_f32_16x16x32_bf16 v[28:31], v[196:199], v[138:141], v[28:31]
	v_mfma_f32_16x16x32_bf16 v[24:27], v[196:199], v[142:145], v[24:27]
	v_mfma_f32_16x16x32_bf16 v[20:23], v[196:199], v[146:149], v[20:23]
	v_mfma_f32_16x16x32_bf16 v[16:19], v[196:199], v[150:153], v[16:19]
	s_waitcnt lgkmcnt(1)
	v_mfma_f32_16x16x32_bf16 v[12:15], v[200:203], v[138:141], v[12:15]
	v_mfma_f32_16x16x32_bf16 v[8:11], v[200:203], v[142:145], v[8:11]
	v_mfma_f32_16x16x32_bf16 v[4:7], v[200:203], v[146:149], v[4:7]
	v_mfma_f32_16x16x32_bf16 v[0:3], v[200:203], v[150:153], v[0:3]
	s_waitcnt lgkmcnt(0)
	v_mfma_f32_16x16x32_bf16 v[88:91], v[204:207], v[138:141], v[88:91]
	v_mfma_f32_16x16x32_bf16 v[92:95], v[204:207], v[142:145], v[92:95]
	v_mfma_f32_16x16x32_bf16 v[100:103], v[204:207], v[146:149], v[100:103]
	v_mfma_f32_16x16x32_bf16 v[104:107], v[204:207], v[150:153], v[104:107]
	s_setprio 0
	s_add_i32 s16, s60, 1
	s_cmp_lg_u32 s60, 2
	s_cselect_b32 s60, s16, 0
	s_add_u32 s50, s50, 64
	s_addc_u32 s51, s51, 0
	s_cmpk_eq_i32 s50, 0x780
	s_cbranch_scc0 .LBB0_477
	s_mul_i32 s16, s60, 0x6000
	v_add_u32_e32 v137, s16, v135
	v_add_u32_e32 v150, v137, v128
	v_add_u32_e32 v137, v137, v136
	s_waitcnt vmcnt(6)
	s_waitcnt vmcnt(0)
	s_barrier
; template <bool TRANS, class Epi>
; DEVI int g2_body(const G2Tile& t, int st, char* smem, bool has_next, const G2Tile& nxt, const Epi& epi) {
;     ...
;     for (int kt = 0; kt < nk; ++kt) {
;         if (kt + 1 < nk) asm volatile("s_waitcnt vmcnt(6)" ::: "memory");
;         else asm volatile("s_waitcnt vmcnt(0)" ::: "memory");
;         __syncthreads();
;         if (kt + 2 < nk) g2_issue(t, kt + 2, st >= 1 ? st - 1 : 2, smem);
;         const char* sa = smem + st * 24576 + frag;
;         bf16x8 bfr[4];
; #pragma unroll
;         for (int n = 0; n < 4; ++n) bfr[n] = *(const bf16x8*)(sa + (16 + wc * 4 + n) * 1024);
; #pragma unroll
;         for (int mh = 0; mh < 2; ++mh) {
;             bf16x8 af[4];
; #pragma unroll
;             for (int m = 0; m < 4; ++m) af[m] = *(const bf16x8*)(sa + (wr * 8 + mh * 4 + m) * 1024);
;             __builtin_amdgcn_s_setprio(1);
; #pragma unroll
;             for (int m = 0; m < 4; ++m)
; #pragma unroll
;                 for (int n = 0; n < 4; ++n)
;                     acc[mh * 4 + m][n] = TRANS ? __builtin_amdgcn_mfma_f32_16x16x32_bf16(bfr[n], af[m], acc[mh * 4 + m][n], 0, 0, 0)
;                                                : __builtin_amdgcn_mfma_f32_16x16x32_bf16(af[m], bfr[n], acc[mh * 4 + m][n], 0, 0, 0);
;             __builtin_amdgcn_s_setprio(0);
;         }
;         st = st == 2 ? 0 : st + 1;
;     }
;     if (has_next) g2_prologue(nxt, st, smem);
	ds_read_b128 v[138:141], v150 offset:16384
	ds_read_b128 v[142:145], v150 offset:17408
	ds_read_b128 v[146:149], v150 offset:18432
	ds_read_b128 v[150:153], v150 offset:19456
	ds_read_b128 v[154:157], v137
	ds_read_b128 v[158:161], v137 offset:1024
	ds_read_b128 v[162:165], v137 offset:2048
	ds_read_b128 v[166:169], v137 offset:3072
	s_setprio 1
	s_waitcnt lgkmcnt(3)
	v_mfma_f32_16x16x32_bf16 v[124:127], v[154:157], v[138:141], v[124:127]
	v_mfma_f32_16x16x32_bf16 v[120:123], v[154:157], v[142:145], v[120:123]
	v_mfma_f32_16x16x32_bf16 v[116:119], v[154:157], v[146:149], v[116:119]
	v_mfma_f32_16x16x32_bf16 v[112:115], v[154:157], v[150:153], v[112:115]
	s_waitcnt lgkmcnt(2)
	v_mfma_f32_16x16x32_bf16 v[108:111], v[158:161], v[138:141], v[108:111]
	v_mfma_f32_16x16x32_bf16 v[96:99], v[158:161], v[142:145], v[96:99]
	v_mfma_f32_16x16x32_bf16 v[84:87], v[158:161], v[146:149], v[84:87]
	v_mfma_f32_16x16x32_bf16 v[80:83], v[158:161], v[150:153], v[80:83]
	s_waitcnt lgkmcnt(1)
	v_mfma_f32_16x16x32_bf16 v[76:79], v[162:165], v[138:141], v[76:79]
	v_mfma_f32_16x16x32_bf16 v[72:75], v[162:165], v[142:145], v[72:75]
	v_mfma_f32_16x16x32_bf16 v[68:71], v[162:165], v[146:149], v[68:71]
	v_mfma_f32_16x16x32_bf16 v[64:67], v[162:165], v[150:153], v[64:67]
	s_waitcnt lgkmcnt(0)
	v_mfma_f32_16x16x32_bf16 v[60:63], v[166:169], v[138:141], v[60:63]
	v_mfma_f32_16x16x32_bf16 v[56:59], v[166:169], v[142:145], v[56:59]
	v_mfma_f32_16x16x32_bf16 v[52:55], v[166:169], v[146:149], v[52:55]
	v_mfma_f32_16x16x32_bf16 v[48:51], v[166:169], v[150:153], v[48:51]
	s_setprio 0
	ds_read_b128 v[154:157], v137 offset:4096
	ds_read_b128 v[158:161], v137 offset:5120
	ds_read_b128 v[162:165], v137 offset:6144
	ds_read_b128 v[166:169], v137 offset:7168
	s_setprio 1
	s_waitcnt lgkmcnt(3)
	v_mfma_f32_16x16x32_bf16 v[44:47], v[154:157], v[138:141], v[44:47]
	v_mfma_f32_16x16x32_bf16 v[40:43], v[154:157], v[142:145], v[40:43]
	v_mfma_f32_16x16x32_bf16 v[36:39], v[154:157], v[146:149], v[36:39]
	v_mfma_f32_16x16x32_bf16 v[32:35], v[154:157], v[150:153], v[32:35]
	s_waitcnt lgkmcnt(2)
	v_mfma_f32_16x16x32_bf16 v[28:31], v[158:161], v[138:141], v[28:31]
	v_mfma_f32_16x16x32_bf16 v[24:27], v[158:161], v[142:145], v[24:27]
	v_mfma_f32_16x16x32_bf16 v[20:23], v[158:161], v[146:149], v[20:23]
	v_mfma_f32_16x16x32_bf16 v[16:19], v[158:161], v[150:153], v[16:19]
	s_waitcnt lgkmcnt(1)
	v_mfma_f32_16x16x32_bf16 v[12:15], v[162:165], v[138:141], v[12:15]
	v_mfma_f32_16x16x32_bf16 v[8:11], v[162:165], v[142:145], v[8:11]
	v_mfma_f32_16x16x32_bf16 v[4:7], v[162:165], v[146:149], v[4:7]
	v_mfma_f32_16x16x32_bf16 v[0:3], v[162:165], v[150:153], v[0:3]
	s_waitcnt lgkmcnt(0)
	v_mfma_f32_16x16x32_bf16 v[138:141], v[166:169], v[138:141], v[88:91]
	v_mfma_f32_16x16x32_bf16 v[142:145], v[166:169], v[142:145], v[92:95]
	v_mfma_f32_16x16x32_bf16 v[146:149], v[166:169], v[146:149], v[100:103]
	v_mfma_f32_16x16x32_bf16 v[150:153], v[166:169], v[150:153], v[104:107]
	s_setprio 0
	s_add_i32 s16, s60, 1
	s_cmp_lg_u32 s60, 2
	s_cselect_b32 s16, s16, 0
	s_mul_i32 s17, s16, 0x6000
	v_add_u32_e32 v100, s17, v135
	v_add_u32_e32 v135, v100, v136
	v_add_u32_e32 v100, v100, v128
	s_waitcnt vmcnt(0)
	s_barrier
	ds_read_b128 v[154:157], v135 offset:3072
	ds_read_b128 v[158:161], v135 offset:2048
	ds_read_b128 v[88:91], v135 offset:1024
	ds_read_b128 v[92:95], v135
	ds_read_b128 v[162:165], v100 offset:19456
	ds_read_b128 v[166:169], v100 offset:18432
	ds_read_b128 v[184:187], v100 offset:17408
	ds_read_b128 v[188:191], v100 offset:16384
	s_setprio 1
	s_waitcnt lgkmcnt(0)
	v_mfma_f32_16x16x32_bf16 v[124:127], v[92:95], v[188:191], v[124:127]
	v_mfma_f32_16x16x32_bf16 v[120:123], v[92:95], v[184:187], v[120:123]
	v_mfma_f32_16x16x32_bf16 v[116:119], v[92:95], v[166:169], v[116:119]
	v_mfma_f32_16x16x32_bf16 v[112:115], v[92:95], v[162:165], v[112:115]
	v_mfma_f32_16x16x32_bf16 v[108:111], v[88:91], v[188:191], v[108:111]
	v_mfma_f32_16x16x32_bf16 v[104:107], v[88:91], v[184:187], v[96:99]
	v_mfma_f32_16x16x32_bf16 v[100:103], v[88:91], v[166:169], v[84:87]
	v_mfma_f32_16x16x32_bf16 v[96:99], v[88:91], v[162:165], v[80:83]
	v_mfma_f32_16x16x32_bf16 v[92:95], v[158:161], v[188:191], v[76:79]
	v_mfma_f32_16x16x32_bf16 v[88:91], v[158:161], v[184:187], v[72:75]
	v_mfma_f32_16x16x32_bf16 v[84:87], v[158:161], v[166:169], v[68:71]
	v_mfma_f32_16x16x32_bf16 v[80:83], v[158:161], v[162:165], v[64:67]
	v_mfma_f32_16x16x32_bf16 v[76:79], v[154:157], v[188:191], v[60:63]
	v_mfma_f32_16x16x32_bf16 v[72:75], v[154:157], v[184:187], v[56:59]
	v_mfma_f32_16x16x32_bf16 v[68:71], v[154:157], v[166:169], v[52:55]
	v_mfma_f32_16x16x32_bf16 v[64:67], v[154:157], v[162:165], v[48:51]
	s_setprio 0
	s_nop 1
	ds_read_b128 v[48:51], v135 offset:4096
	ds_read_b128 v[154:157], v135 offset:5120
	ds_read_b128 v[158:161], v135 offset:6144
	ds_read_b128 v[192:195], v135 offset:7168
	s_setprio 1
	s_waitcnt lgkmcnt(3)
	v_mfma_f32_16x16x32_bf16 v[60:63], v[48:51], v[188:191], v[44:47]
	v_mfma_f32_16x16x32_bf16 v[56:59], v[48:51], v[184:187], v[40:43]
	v_mfma_f32_16x16x32_bf16 v[52:55], v[48:51], v[166:169], v[36:39]
	v_mfma_f32_16x16x32_bf16 v[48:51], v[48:51], v[162:165], v[32:35]
	s_waitcnt lgkmcnt(2)
	v_mfma_f32_16x16x32_bf16 v[44:47], v[154:157], v[188:191], v[28:31]
	v_mfma_f32_16x16x32_bf16 v[40:43], v[154:157], v[184:187], v[24:27]
	v_mfma_f32_16x16x32_bf16 v[36:39], v[154:157], v[166:169], v[20:23]
	v_mfma_f32_16x16x32_bf16 v[32:35], v[154:157], v[162:165], v[16:19]
	s_waitcnt lgkmcnt(1)
	v_mfma_f32_16x16x32_bf16 v[28:31], v[158:161], v[188:191], v[12:15]
	v_mfma_f32_16x16x32_bf16 v[24:27], v[158:161], v[184:187], v[8:11]
	v_mfma_f32_16x16x32_bf16 v[20:23], v[158:161], v[166:169], v[4:7]
	v_mfma_f32_16x16x32_bf16 v[16:19], v[158:161], v[162:165], v[0:3]
	s_waitcnt lgkmcnt(0)
	v_mfma_f32_16x16x32_bf16 v[12:15], v[192:195], v[188:191], v[138:141]
	v_mfma_f32_16x16x32_bf16 v[8:11], v[192:195], v[184:187], v[142:145]
	v_mfma_f32_16x16x32_bf16 v[4:7], v[192:195], v[166:169], v[146:149]
	v_mfma_f32_16x16x32_bf16 v[0:3], v[192:195], v[162:165], v[150:153]
	s_setprio 0
	s_add_i32 s17, s16, 1
	s_cmp_lg_u32 s16, 2
	s_cselect_b32 s60, s17, 0
	s_and_b64 vcc, exec, s[42:43]
	s_cbranch_vccz .LBB0_473
; DEVI int opaque_tid() { int t = (int)threadIdx.x; asm volatile("" : "+v"(t)); return t; }
; DEVI void g2_issue(const G2Tile& t, int kt, int st, char* smem) {
;     const int tid = opaque_tid(), lane = tid & 63, w = tid >> 6;
;     const int rr = lane >> 2, sch = (lane & 3) ^ ((lane >> 5) << 1);
;     const bf16_t* ap = t.A + (size_t)kt * 32 + (size_t)(w * 16 + rr) * t.lda + sch * 8;
;     const bf16_t* bp = t.Bt + (size_t)kt * 32 + (size_t)(w * 16 + rr) * t.ldb + sch * 8;
;     char* sa = smem + st * 24576 + w * 1024 + lane * 16;
; #pragma unroll
;     for (int i = 0; i < 4; ++i) __builtin_amdgcn_global_load_lds((const unsigned*)(ap + (size_t)(64 * i) * t.lda), (unsigned*)(sa + i * 4096), 16, 0, 0);
; #pragma unroll
;     for (int i = 0; i < 2; ++i) __builtin_amdgcn_global_load_lds((const unsigned*)(bp + (size_t)(64 * i) * t.ldb), (unsigned*)(sa + 16384 + i * 4096), 16, 0, 0);
; }
; DEVI void g2_prologue(const G2Tile& t, int st, char* smem) {
;     g2_issue(t, 0, st, smem);
;     g2_issue(t, 1, st == 2 ? 0 : st + 1, smem);
; }
	v_mov_b32_e32 v128, v172
	s_mul_i32 s16, s60, 0x6000
	v_ashrrev_i32_e32 v140, 6, v128
	v_bfe_u32 v136, v128, 2, 4
	v_and_b32_e32 v135, 63, v128
	v_and_b32_e32 v137, 3, v128
	v_lshrrev_b32_e32 v128, 4, v128
	v_lshl_or_b32 v136, v140, 4, v136
	v_bitop3_b32 v128, v128, v137, 2 bitop3:0x6c
	v_ashrrev_i32_e32 v137, 31, v136
	s_add_i32 s17, s16, 0
	v_lshlrev_b32_e32 v140, 10, v140
	v_lshlrev_b32_e32 v135, 4, v135
	v_lshlrev_b64 v[136:137], 11, v[136:137]
	v_add3_u32 v135, s17, v140, v135
	v_lshl_add_u64 v[138:139], s[22:23], 0, v[136:137]
	v_lshlrev_b32_e32 v128, 4, v128
	v_readfirstlane_b32 s17, v135
	v_add_u32_e32 v142, 0x1000, v135
	v_lshl_add_u64 v[138:139], v[138:139], 0, v[128:129]
	s_mov_b32 m0, s17
	v_readfirstlane_b32 s17, v142
	v_add_u32_e32 v142, 0x2000, v135
	global_load_lds_dwordx4 v[138:139], off
	v_lshl_add_u64 v[140:141], v[138:139], 0, s[0:1]
	s_mov_b32 m0, s17
	v_readfirstlane_b32 s17, v142
	global_load_lds_dwordx4 v[140:141], off
	v_lshl_add_u64 v[140:141], v[138:139], 0, s[2:3]
	s_mov_b32 m0, s17
	v_lshl_add_u64 v[136:137], s[24:25], 0, v[136:137]
	global_load_lds_dwordx4 v[140:141], off
	v_add_u32_e32 v140, 0x3000, v135
	v_lshl_add_u64 v[136:137], v[136:137], 0, v[128:129]
	v_readfirstlane_b32 s17, v140
	v_add_u32_e32 v128, 0x4000, v135
	v_lshl_add_u64 v[138:139], v[138:139], 0, s[4:5]
	s_mov_b32 m0, s17
	v_readfirstlane_b32 s17, v128
	v_add_u32_e32 v128, 0x5000, v135
	global_load_lds_dwordx4 v[138:139], off
	s_mov_b32 m0, s17
	v_readfirstlane_b32 s17, v128
	global_load_lds_dwordx4 v[136:137], off
	v_lshl_add_u64 v[136:137], v[136:137], 0, s[0:1]
	s_mov_b32 m0, s17
	v_mov_b32_e32 v128, v172
	global_load_lds_dwordx4 v[136:137], off
	s_addk_i32 s16, 0x6000
	v_ashrrev_i32_e32 v142, 6, v128
	v_bfe_u32 v136, v128, 2, 4
	v_and_b32_e32 v135, 63, v128
	v_and_b32_e32 v137, 3, v128
	v_lshrrev_b32_e32 v128, 4, v128
	v_lshl_or_b32 v136, v142, 4, v136
	s_cmp_lg_u32 s60, 2
	v_bitop3_b32 v128, v128, v137, 2 bitop3:0x6c
	v_ashrrev_i32_e32 v137, 31, v136
	s_cselect_b32 s16, s16, 0
	v_lshlrev_b64 v[136:137], 11, v[136:137]
	s_add_i32 s16, s16, 0
	v_lshlrev_b32_e32 v142, 10, v142
	v_lshlrev_b32_e32 v135, 4, v135
	v_lshl_add_u64 v[138:139], s[22:23], 0, v[136:137]
	v_lshlrev_b32_e32 v128, 4, v128
	v_add3_u32 v135, s16, v142, v135
	v_lshl_add_u64 v[138:139], v[138:139], 0, v[128:129]
	v_readfirstlane_b32 s16, v135
	v_add_u32_e32 v142, 0x1000, v135
	v_lshl_add_u64 v[140:141], v[138:139], 0, 64
	s_mov_b32 m0, s16
	v_readfirstlane_b32 s16, v142
	v_add_u32_e32 v142, 0x2000, v135
	global_load_lds_dwordx4 v[140:141], off
	v_lshl_add_u64 v[140:141], v[138:139], 0, s[6:7]
	s_mov_b32 m0, s16
	v_readfirstlane_b32 s16, v142
	global_load_lds_dwordx4 v[140:141], off
	v_lshl_add_u64 v[140:141], v[138:139], 0, s[8:9]
	s_mov_b32 m0, s16
	v_lshl_add_u64 v[136:137], s[24:25], 0, v[136:137]
	global_load_lds_dwordx4 v[140:141], off
	v_add_u32_e32 v140, 0x3000, v135
	v_lshl_add_u64 v[136:137], v[136:137], 0, v[128:129]
	v_readfirstlane_b32 s16, v140
	v_add_u32_e32 v128, 0x4000, v135
	v_lshl_add_u64 v[138:139], v[138:139], 0, s[10:11]
	s_mov_b32 m0, s16
	v_readfirstlane_b32 s16, v128
	v_add_u32_e32 v128, 0x5000, v135
	global_load_lds_dwordx4 v[138:139], off
	v_lshl_add_u64 v[138:139], v[136:137], 0, 64
	s_mov_b32 m0, s16
	v_readfirstlane_b32 s16, v128
	global_load_lds_dwordx4 v[138:139], off
	v_lshl_add_u64 v[136:137], v[136:137], 0, s[6:7]
	s_mov_b32 m0, s16
	s_nop 0
	global_load_lds_dwordx4 v[136:137], off
	s_branch .LBB0_473

; DEVI int opaque_tid() { int t = (int)threadIdx.x; asm volatile("" : "+v"(t)); return t; }
; DEVI void g2_issue(const G2Tile& t, int kt, int st, char* smem) {
;     const int tid = opaque_tid(), lane = tid & 63, w = tid >> 6;
;     const int rr = lane >> 2, sch = (lane & 3) ^ ((lane >> 5) << 1);
;     const bf16_t* ap = t.A + (size_t)kt * 32 + (size_t)(w * 16 + rr) * t.lda + sch * 8;
;     const bf16_t* bp = t.Bt + (size_t)kt * 32 + (size_t)(w * 16 + rr) * t.ldb + sch * 8;
;     char* sa = smem + st * 24576 + w * 1024 + lane * 16;
; #pragma unroll
;     for (int i = 0; i < 4; ++i) __builtin_amdgcn_global_load_lds((const unsigned*)(ap + (size_t)(64 * i) * t.lda), (unsigned*)(sa + i * 4096), 16, 0, 0);
; #pragma unroll
;     for (int i = 0; i < 2; ++i) __builtin_amdgcn_global_load_lds((const unsigned*)(bp + (size_t)(64 * i) * t.ldb), (unsigned*)(sa + 16384 + i * 4096), 16, 0, 0);
; }
; DEVI void g2_prologue(const G2Tile& t, int st, char* smem) {
;     g2_issue(t, 0, st, smem);
;     g2_issue(t, 1, st == 2 ? 0 : st + 1, smem);
; }
; template <bool TRANS, class Epi>
; DEVI int g2_body(const G2Tile& t, int st, char* smem, bool has_next, const G2Tile& nxt, const Epi& epi) {
;     const int tid = opaque_tid(), lane = tid & 63, w = tid >> 6, wr = w >> 1, wc = w & 1, fr = lane & 15, fq = lane >> 4;
;     f32x4 acc[8][4];
; #pragma unroll
;     for (int m = 0; m < 8; ++m)
; #pragma unroll
;         for (int n = 0; n < 4; ++n) acc[m][n] = (f32x4){0.f, 0.f, 0.f, 0.f};
;     const int frag = fr * 64 + ((fq ^ ((fr >> 3) << 1)) << 4);
;     const int nk = t.nk;
.LBB0_818:
	v_mov_b32_e32 v128, v172
	s_mov_b64 s[34:35], 0
	s_waitcnt vmcnt(0)
	v_lshrrev_b32_e32 v3, 2, v128
	v_lshrrev_b32_e32 v0, 4, v128
	v_and_b32_e32 v3, 2, v3
	v_lshlrev_b32_e32 v1, 6, v128
	v_bitop3_b32 v0, v0, v3, 3 bitop3:0x6c
	v_and_b32_e32 v2, 0x3c0, v1
	v_lshlrev_b32_e32 v0, 4, v0
	v_bfe_u32 v129, v128, 6, 1
	v_add3_u32 v132, 0, v2, v0
	v_mov_b32_e32 v0, 0
	v_bfe_u32 v130, v128, 4, 2
	v_lshlrev_b32_e32 v131, 12, v129
	v_and_b32_e32 v133, 0xffffe000, v1
	v_mov_b32_e32 v1, v0
	v_mov_b32_e32 v2, v0
	v_mov_b32_e32 v3, v0
	v_mov_b32_e32 v4, v0
	v_mov_b32_e32 v5, v0
	v_mov_b32_e32 v6, v0
	v_mov_b32_e32 v7, v0
	v_mov_b32_e32 v8, v0
	v_mov_b32_e32 v9, v0
	v_mov_b32_e32 v10, v0
	v_mov_b32_e32 v11, v0
	v_mov_b32_e32 v12, v0
	v_mov_b32_e32 v13, v0
	v_mov_b32_e32 v14, v0
	v_mov_b32_e32 v15, v0
	v_mov_b32_e32 v16, v0
	v_mov_b32_e32 v17, v0
	v_mov_b32_e32 v18, v0
	v_mov_b32_e32 v19, v0
	v_mov_b32_e32 v20, v0
	v_mov_b32_e32 v21, v0
	v_mov_b32_e32 v22, v0
	v_mov_b32_e32 v23, v0
	v_mov_b32_e32 v24, v0
	v_mov_b32_e32 v25, v0
	v_mov_b32_e32 v26, v0
	v_mov_b32_e32 v27, v0
	v_mov_b32_e32 v28, v0
	v_mov_b32_e32 v29, v0
	v_mov_b32_e32 v30, v0
	v_mov_b32_e32 v31, v0
	v_mov_b32_e32 v32, v0
	v_mov_b32_e32 v33, v0
	v_mov_b32_e32 v34, v0
	v_mov_b32_e32 v35, v0
	v_mov_b32_e32 v36, v0
	v_mov_b32_e32 v37, v0
	v_mov_b32_e32 v38, v0
	v_mov_b32_e32 v39, v0
	v_mov_b32_e32 v40, v0
	v_mov_b32_e32 v41, v0
	v_mov_b32_e32 v42, v0
	v_mov_b32_e32 v43, v0
	v_mov_b32_e32 v44, v0
	v_mov_b32_e32 v45, v0
	v_mov_b32_e32 v46, v0
	v_mov_b32_e32 v47, v0
	v_mov_b32_e32 v48, v0
	v_mov_b32_e32 v49, v0
	v_mov_b32_e32 v50, v0
	v_mov_b32_e32 v51, v0
	v_mov_b32_e32 v52, v0
	v_mov_b32_e32 v53, v0
	v_mov_b32_e32 v54, v0
	v_mov_b32_e32 v55, v0
	v_mov_b32_e32 v56, v0
	v_mov_b32_e32 v57, v0
	v_mov_b32_e32 v58, v0
	v_mov_b32_e32 v59, v0
	v_mov_b32_e32 v60, v0
	v_mov_b32_e32 v61, v0
	v_mov_b32_e32 v62, v0
	v_mov_b32_e32 v63, v0
	v_mov_b32_e32 v64, v0
	v_mov_b32_e32 v65, v0
	v_mov_b32_e32 v66, v0
	v_mov_b32_e32 v67, v0
	v_mov_b32_e32 v68, v0
	v_mov_b32_e32 v69, v0
	v_mov_b32_e32 v70, v0
	v_mov_b32_e32 v71, v0
	v_mov_b32_e32 v72, v0
	v_mov_b32_e32 v73, v0
	v_mov_b32_e32 v74, v0
	v_mov_b32_e32 v75, v0
	v_mov_b32_e32 v76, v0
	v_mov_b32_e32 v77, v0
	v_mov_b32_e32 v78, v0
	v_mov_b32_e32 v79, v0
	v_mov_b32_e32 v80, v0
	v_mov_b32_e32 v81, v0
	v_mov_b32_e32 v82, v0
	v_mov_b32_e32 v83, v0
	v_mov_b32_e32 v84, v0
	v_mov_b32_e32 v85, v0
	v_mov_b32_e32 v86, v0
	v_mov_b32_e32 v87, v0
	v_mov_b32_e32 v96, v0
	v_mov_b32_e32 v97, v0
	v_mov_b32_e32 v98, v0
	v_mov_b32_e32 v99, v0
	v_mov_b32_e32 v108, v0
	v_mov_b32_e32 v109, v0
	v_mov_b32_e32 v110, v0
	v_mov_b32_e32 v111, v0
	v_mov_b32_e32 v112, v0
	v_mov_b32_e32 v113, v0
	v_mov_b32_e32 v114, v0
	v_mov_b32_e32 v115, v0
	v_mov_b32_e32 v116, v0
	v_mov_b32_e32 v117, v0
	v_mov_b32_e32 v118, v0
	v_mov_b32_e32 v119, v0
	v_mov_b32_e32 v120, v0
	v_mov_b32_e32 v121, v0
	v_mov_b32_e32 v122, v0
	v_mov_b32_e32 v123, v0
	v_mov_b32_e32 v124, v0
	v_mov_b32_e32 v125, v0
	v_mov_b32_e32 v126, v0
	v_mov_b32_e32 v127, v0
	v_mov_b32_e32 v88, v0
	v_mov_b32_e32 v89, v0
	v_mov_b32_e32 v90, v0
	v_mov_b32_e32 v91, v0
	v_mov_b32_e32 v92, v0
	v_mov_b32_e32 v93, v0
	v_mov_b32_e32 v94, v0
	v_mov_b32_e32 v95, v0
	v_mov_b32_e32 v100, v0
	v_mov_b32_e32 v101, v0
	v_mov_b32_e32 v102, v0
	v_mov_b32_e32 v103, v0
	v_mov_b32_e32 v104, v0
	v_mov_b32_e32 v105, v0
	v_mov_b32_e32 v106, v0
	v_mov_b32_e32 v107, v0
	v_and_b32_e32 v224, 3, v172
	v_lshrrev_b32_e32 v225, 4, v172
	v_bitop3_b32 v224, v225, v224, 2 bitop3:0x6c
	v_ashrrev_i32_e32 v225, 6, v172
	v_bfe_u32 v222, v172, 2, 4
	v_readfirstlane_b32 s32, v225
	v_lshl_or_b32 v222, v225, 4, v222
	v_lshlrev_b32_e32 v222, 11, v222
	v_lshl_or_b32 v222, v224, 4, v222
	v_mov_b32_e32 v223, 0
	s_lshl_b32 s32, s32, 10
	v_lshl_add_u64 v[208:209], s[28:29], 0, v[222:223]
	v_lshl_add_u64 v[208:209], v[208:209], 0, s[2:3]
	v_lshl_add_u64 v[210:211], s[28:29], 0, v[222:223]
	v_lshl_add_u64 v[210:211], v[210:211], 0, s[4:5]
	v_lshl_add_u64 v[212:213], s[28:29], 0, v[222:223]
	s_mov_b64 s[98:99], 0x40080
	v_lshl_add_u64 v[212:213], v[212:213], 0, s[98:99]
	v_lshl_add_u64 v[214:215], s[28:29], 0, v[222:223]
	s_mov_b64 s[98:99], 0x60080
	v_lshl_add_u64 v[214:215], v[214:215], 0, s[98:99]
	v_lshl_add_u64 v[218:219], s[30:31], 0, v[222:223]
	v_lshl_add_u64 v[218:219], v[218:219], 0, s[2:3]
	v_lshl_add_u64 v[220:221], s[30:31], 0, v[222:223]
	v_lshl_add_u64 v[220:221], v[220:221], 0, s[4:5]
; DEVI int opaque_tid() { int t = (int)threadIdx.x; asm volatile("" : "+v"(t)); return t; }
; DEVI void g2_issue(const G2Tile& t, int kt, int st, char* smem) {
;     const int tid = opaque_tid(), lane = tid & 63, w = tid >> 6;
;     const int rr = lane >> 2, sch = (lane & 3) ^ ((lane >> 5) << 1);
;     const bf16_t* ap = t.A + (size_t)kt * 32 + (size_t)(w * 16 + rr) * t.lda + sch * 8;
;     const bf16_t* bp = t.Bt + (size_t)kt * 32 + (size_t)(w * 16 + rr) * t.ldb + sch * 8;
;     char* sa = smem + st * 24576 + w * 1024 + lane * 16;
; #pragma unroll
;     for (int i = 0; i < 4; ++i) __builtin_amdgcn_global_load_lds((const unsigned*)(ap + (size_t)(64 * i) * t.lda), (unsigned*)(sa + i * 4096), 16, 0, 0);
; #pragma unroll
;     for (int i = 0; i < 2; ++i) __builtin_amdgcn_global_load_lds((const unsigned*)(bp + (size_t)(64 * i) * t.ldb), (unsigned*)(sa + 16384 + i * 4096), 16, 0, 0);
; }
; template <bool TRANS, class Epi>
; DEVI int g2_body(const G2Tile& t, int st, char* smem, bool has_next, const G2Tile& nxt, const Epi& epi) {
;     ...
;     for (int kt = 0; kt < nk; ++kt) {
;         if (kt + 1 < nk) asm volatile("s_waitcnt vmcnt(6)" ::: "memory");
;         else asm volatile("s_waitcnt vmcnt(0)" ::: "memory");
;         __syncthreads();
;         if (kt + 2 < nk) g2_issue(t, kt + 2, st >= 1 ? st - 1 : 2, smem);
;         const char* sa = smem + st * 24576 + frag;
;         bf16x8 bfr[4];
; #pragma unroll
;         for (int n = 0; n < 4; ++n) bfr[n] = *(const bf16x8*)(sa + (16 + wc * 4 + n) * 1024);
; #pragma unroll
;         for (int mh = 0; mh < 2; ++mh) {
;             bf16x8 af[4];
; #pragma unroll
;             for (int m = 0; m < 4; ++m) af[m] = *(const bf16x8*)(sa + (wr * 8 + mh * 4 + m) * 1024);
;             __builtin_amdgcn_s_setprio(1);
; #pragma unroll
;             for (int m = 0; m < 4; ++m)
; #pragma unroll
;                 for (int n = 0; n < 4; ++n)
;                     acc[mh * 4 + m][n] = TRANS ? __builtin_amdgcn_mfma_f32_16x16x32_bf16(bfr[n], af[m], acc[mh * 4 + m][n], 0, 0, 0)
;                                                : __builtin_amdgcn_mfma_f32_16x16x32_bf16(af[m], bfr[n], acc[mh * 4 + m][n], 0, 0, 0);
;             __builtin_amdgcn_s_setprio(0);
;         }
;         st = st == 2 ? 0 : st + 1;
;     }
.LBB0_819:
	s_waitcnt vmcnt(6)
	s_waitcnt lgkmcnt(0)
	s_barrier
	s_mul_i32 s26, s72, 0x6000
	s_add_i32 s33, s26, 0xffffa000
	s_cmp_gt_i32 s72, 0
	s_cselect_b32 s33, s33, 0xc000
	s_add_i32 s33, s33, s32
	v_add_u32_e32 v150, s26, v132
	v_add_u32_e32 v146, v150, v131
	v_add_u32_e32 v166, v150, v133
	ds_read_b128 v[134:137], v146 offset:16384
	ds_read_b128 v[138:141], v146 offset:17408
	ds_read_b128 v[142:145], v146 offset:18432
	ds_read_b128 v[146:149], v146 offset:19456
	ds_read_b128 v[150:153], v166
	ds_read_b128 v[154:157], v166 offset:1024
	ds_read_b128 v[158:161], v166 offset:2048
	ds_read_b128 v[162:165], v166 offset:3072
	ds_read_b128 v[192:195], v166 offset:4096
	ds_read_b128 v[196:199], v166 offset:5120
	ds_read_b128 v[200:203], v166 offset:6144
	ds_read_b128 v[204:207], v166 offset:7168
	s_mov_b32 m0, s33
	s_nop 0
	global_load_lds_dwordx4 v[208:209], off
	v_lshl_add_u64 v[208:209], v[208:209], 0, 64
	s_add_i32 m0, s33, 0x1000
	s_setprio 1
	s_waitcnt lgkmcnt(7)
	v_mfma_f32_16x16x32_bf16 v[124:127], v[134:137], v[150:153], v[124:127]
	v_mfma_f32_16x16x32_bf16 v[120:123], v[138:141], v[150:153], v[120:123]
	v_mfma_f32_16x16x32_bf16 v[116:119], v[142:145], v[150:153], v[116:119]
	v_mfma_f32_16x16x32_bf16 v[112:115], v[146:149], v[150:153], v[112:115]
	global_load_lds_dwordx4 v[210:211], off
	v_lshl_add_u64 v[210:211], v[210:211], 0, 64
	s_add_i32 m0, s33, 0x2000
	s_waitcnt lgkmcnt(6)
	v_mfma_f32_16x16x32_bf16 v[108:111], v[134:137], v[154:157], v[108:111]
	v_mfma_f32_16x16x32_bf16 v[96:99], v[138:141], v[154:157], v[96:99]
	v_mfma_f32_16x16x32_bf16 v[84:87], v[142:145], v[154:157], v[84:87]
	v_mfma_f32_16x16x32_bf16 v[80:83], v[146:149], v[154:157], v[80:83]
	global_load_lds_dwordx4 v[212:213], off
	v_lshl_add_u64 v[212:213], v[212:213], 0, 64
	s_add_i32 m0, s33, 0x3000
	s_waitcnt lgkmcnt(5)
	v_mfma_f32_16x16x32_bf16 v[76:79], v[134:137], v[158:161], v[76:79]
	v_mfma_f32_16x16x32_bf16 v[72:75], v[138:141], v[158:161], v[72:75]
	v_mfma_f32_16x16x32_bf16 v[68:71], v[142:145], v[158:161], v[68:71]
	v_mfma_f32_16x16x32_bf16 v[64:67], v[146:149], v[158:161], v[64:67]
	global_load_lds_dwordx4 v[214:215], off
	v_lshl_add_u64 v[214:215], v[214:215], 0, 64
	s_add_i32 m0, s33, 0x4000
	s_waitcnt lgkmcnt(4)
	v_mfma_f32_16x16x32_bf16 v[60:63], v[134:137], v[162:165], v[60:63]
	v_mfma_f32_16x16x32_bf16 v[56:59], v[138:141], v[162:165], v[56:59]
	v_mfma_f32_16x16x32_bf16 v[52:55], v[142:145], v[162:165], v[52:55]
	v_mfma_f32_16x16x32_bf16 v[48:51], v[146:149], v[162:165], v[48:51]
	global_load_lds_dwordx4 v[218:219], off
	v_lshl_add_u64 v[218:219], v[218:219], 0, 64
	s_add_i32 m0, s33, 0x5000
	s_waitcnt lgkmcnt(3)
	v_mfma_f32_16x16x32_bf16 v[44:47], v[134:137], v[192:195], v[44:47]
	v_mfma_f32_16x16x32_bf16 v[40:43], v[138:141], v[192:195], v[40:43]
	v_mfma_f32_16x16x32_bf16 v[36:39], v[142:145], v[192:195], v[36:39]
	v_mfma_f32_16x16x32_bf16 v[32:35], v[146:149], v[192:195], v[32:35]
	global_load_lds_dwordx4 v[220:221], off
	v_lshl_add_u64 v[220:221], v[220:221], 0, 64
	s_waitcnt lgkmcnt(2)
	v_mfma_f32_16x16x32_bf16 v[28:31], v[134:137], v[196:199], v[28:31]
	v_mfma_f32_16x16x32_bf16 v[24:27], v[138:141], v[196:199], v[24:27]
	v_mfma_f32_16x16x32_bf16 v[20:23], v[142:145], v[196:199], v[20:23]
	v_mfma_f32_16x16x32_bf16 v[16:19], v[146:149], v[196:199], v[16:19]
	s_waitcnt lgkmcnt(1)
	v_mfma_f32_16x16x32_bf16 v[12:15], v[134:137], v[200:203], v[12:15]
	v_mfma_f32_16x16x32_bf16 v[8:11], v[138:141], v[200:203], v[8:11]
	v_mfma_f32_16x16x32_bf16 v[4:7], v[142:145], v[200:203], v[4:7]
	v_mfma_f32_16x16x32_bf16 v[0:3], v[146:149], v[200:203], v[0:3]
	s_waitcnt lgkmcnt(0)
	v_mfma_f32_16x16x32_bf16 v[88:91], v[134:137], v[204:207], v[88:91]
	v_mfma_f32_16x16x32_bf16 v[92:95], v[138:141], v[204:207], v[92:95]
	v_mfma_f32_16x16x32_bf16 v[100:103], v[142:145], v[204:207], v[100:103]
	v_mfma_f32_16x16x32_bf16 v[104:107], v[146:149], v[204:207], v[104:107]
	s_setprio 0
	s_add_i32 s26, s72, 1
	s_cmp_lg_u32 s72, 2
	s_cselect_b32 s72, s26, 0
	s_add_u32 s34, s34, 64
	s_addc_u32 s35, s35, 0
	s_cmpk_lg_i32 s34, 0x780
	s_cbranch_scc1 .LBB0_819
	s_bfe_u32 s71, s36, 0x10005
	s_bfe_u32 s74, s36, 0x20003
	s_lshl_b32 s26, s71, 21
	s_lshl_b32 s28, s74, 19
	s_ashr_i32 s33, s79, 1
	s_and_b32 s75, s63, 0x380
	s_or_b32 s29, s26, s28
	s_add_u32 s30, s90, s29
	s_addc_u32 s31, s91, 0
	s_ashr_i32 s73, s36, 6
	s_add_u32 s26, s19, s26
	s_addc_u32 s29, s42, 0
	s_add_u32 s26, s26, s28
	s_addc_u32 s28, s29, 0
	s_add_u32 s34, s26, 0x400000
	s_mul_i32 s37, s72, 0x6000
	s_addc_u32 s35, s28, 0
	s_lshl_b32 s76, s71, 24
	v_add_u32_e32 v150, s37, v132
	s_add_u32 s26, s43, s76
	v_add_u32_e32 v146, v150, v131
	v_add_u32_e32 v166, v150, v133
	s_addc_u32 s44, s50, 0
	s_lshl_b32 s29, s36, 7
	s_waitcnt vmcnt(6)
	s_waitcnt vmcnt(0)
	s_barrier
; template <bool TRANS, class Epi>
; DEVI int g2_body(const G2Tile& t, int st, char* smem, bool has_next, const G2Tile& nxt, const Epi& epi) {
;     ...
;     for (int kt = 0; kt < nk; ++kt) {
;         if (kt + 1 < nk) asm volatile("s_waitcnt vmcnt(6)" ::: "memory");
;         else asm volatile("s_waitcnt vmcnt(0)" ::: "memory");
;         __syncthreads();
;         if (kt + 2 < nk) g2_issue(t, kt + 2, st >= 1 ? st - 1 : 2, smem);
;         const char* sa = smem + st * 24576 + frag;
;         bf16x8 bfr[4];
; #pragma unroll
;         for (int n = 0; n < 4; ++n) bfr[n] = *(const bf16x8*)(sa + (16 + wc * 4 + n) * 1024);
; #pragma unroll
;         for (int mh = 0; mh < 2; ++mh) {
;             bf16x8 af[4];
; #pragma unroll
;             for (int m = 0; m < 4; ++m) af[m] = *(const bf16x8*)(sa + (wr * 8 + mh * 4 + m) * 1024);
;             __builtin_amdgcn_s_setprio(1);
; #pragma unroll
;             for (int m = 0; m < 4; ++m)
; #pragma unroll
;                 for (int n = 0; n < 4; ++n)
;                     acc[mh * 4 + m][n] = TRANS ? __builtin_amdgcn_mfma_f32_16x16x32_bf16(bfr[n], af[m], acc[mh * 4 + m][n], 0, 0, 0)
;                                                : __builtin_amdgcn_mfma_f32_16x16x32_bf16(af[m], bfr[n], acc[mh * 4 + m][n], 0, 0, 0);
;             __builtin_amdgcn_s_setprio(0);
;         }
;         st = st == 2 ? 0 : st + 1;
	ds_read_b128 v[134:137], v146 offset:16384
	ds_read_b128 v[138:141], v146 offset:17408
	ds_read_b128 v[142:145], v146 offset:18432
	ds_read_b128 v[146:149], v146 offset:19456
	ds_read_b128 v[150:153], v166
	ds_read_b128 v[154:157], v166 offset:1024
	ds_read_b128 v[158:161], v166 offset:2048
	ds_read_b128 v[162:165], v166 offset:3072
	s_lshl_b32 s28, s73, 10
	s_and_b32 s29, s29, 0x380
	s_or_b32 s36, s28, s29
	s_ashr_i32 s37, s36, 31
	s_lshl_b64 s[36:37], s[36:37], 11
	s_add_u32 s36, s26, s36
	s_addc_u32 s37, s44, s37
	s_setprio 1
	s_waitcnt lgkmcnt(3)
	v_mfma_f32_16x16x32_bf16 v[124:127], v[134:137], v[150:153], v[124:127]
	v_mfma_f32_16x16x32_bf16 v[120:123], v[138:141], v[150:153], v[120:123]
	v_mfma_f32_16x16x32_bf16 v[116:119], v[142:145], v[150:153], v[116:119]
	v_mfma_f32_16x16x32_bf16 v[112:115], v[146:149], v[150:153], v[112:115]
	s_waitcnt lgkmcnt(2)
	v_mfma_f32_16x16x32_bf16 v[108:111], v[134:137], v[154:157], v[108:111]
	v_mfma_f32_16x16x32_bf16 v[96:99], v[138:141], v[154:157], v[96:99]
	v_mfma_f32_16x16x32_bf16 v[84:87], v[142:145], v[154:157], v[84:87]
	v_mfma_f32_16x16x32_bf16 v[80:83], v[146:149], v[154:157], v[80:83]
	s_waitcnt lgkmcnt(1)
	v_mfma_f32_16x16x32_bf16 v[76:79], v[134:137], v[158:161], v[76:79]
	v_mfma_f32_16x16x32_bf16 v[72:75], v[138:141], v[158:161], v[72:75]
	s_waitcnt lgkmcnt(0)
	v_mfma_f32_16x16x32_bf16 v[60:63], v[134:137], v[162:165], v[60:63]
	v_mfma_f32_16x16x32_bf16 v[56:59], v[138:141], v[162:165], v[56:59]
	v_mfma_f32_16x16x32_bf16 v[52:55], v[142:145], v[162:165], v[52:55]
	v_mfma_f32_16x16x32_bf16 v[48:51], v[146:149], v[162:165], v[48:51]
	v_mfma_f32_16x16x32_bf16 v[150:153], v[142:145], v[158:161], v[68:71]
	v_mfma_f32_16x16x32_bf16 v[154:157], v[146:149], v[158:161], v[64:67]
	s_setprio 0
	s_nop 1
	ds_read_b128 v[64:67], v166 offset:4096
	ds_read_b128 v[68:71], v166 offset:5120
	ds_read_b128 v[158:161], v166 offset:6144
	ds_read_b128 v[162:165], v166 offset:7168
	s_setprio 1
	s_waitcnt lgkmcnt(3)
	v_mfma_f32_16x16x32_bf16 v[166:169], v[134:137], v[64:67], v[44:47]
	v_mfma_f32_16x16x32_bf16 v[186:189], v[138:141], v[64:67], v[40:43]
	s_waitcnt lgkmcnt(2)
	v_mfma_f32_16x16x32_bf16 v[198:201], v[134:137], v[68:71], v[28:31]
	v_mfma_f32_16x16x32_bf16 v[202:205], v[138:141], v[68:71], v[24:27]
	s_waitcnt lgkmcnt(1)
	v_mfma_f32_16x16x32_bf16 v[218:221], v[134:137], v[158:161], v[12:15]
	v_mfma_f32_16x16x32_bf16 v[222:225], v[138:141], v[158:161], v[8:11]
	v_mfma_f32_16x16x32_bf16 v[4:7], v[142:145], v[158:161], v[4:7]
	v_mfma_f32_16x16x32_bf16 v[0:3], v[146:149], v[158:161], v[0:3]
	s_waitcnt lgkmcnt(0)
	v_mfma_f32_16x16x32_bf16 v[134:137], v[134:137], v[162:165], v[88:91]
	v_mfma_f32_16x16x32_bf16 v[92:95], v[138:141], v[162:165], v[92:95]
	v_mfma_f32_16x16x32_bf16 v[138:141], v[142:145], v[162:165], v[100:103]
	v_mfma_f32_16x16x32_bf16 v[190:193], v[142:145], v[64:67], v[36:39]
	v_mfma_f32_16x16x32_bf16 v[194:197], v[146:149], v[64:67], v[32:35]
	v_mfma_f32_16x16x32_bf16 v[206:209], v[142:145], v[68:71], v[20:23]
	v_mfma_f32_16x16x32_bf16 v[210:213], v[146:149], v[68:71], v[16:19]
	v_mfma_f32_16x16x32_bf16 v[142:145], v[146:149], v[162:165], v[104:107]
	s_setprio 0
	s_add_i32 s26, s72, 1
	s_cmp_lg_u32 s72, 2
	s_cselect_b32 s26, s26, 0
	s_mul_i32 s44, s26, 0x6000
	v_add_u32_e32 v24, s44, v132
	v_add_u32_e32 v88, v24, v133
	v_add_u32_e32 v24, v24, v131
	s_waitcnt vmcnt(0)
	s_barrier
	ds_read_b128 v[8:11], v88 offset:3072
	ds_read_b128 v[12:15], v88 offset:2048
	ds_read_b128 v[16:19], v88 offset:1024
	ds_read_b128 v[20:23], v88
	ds_read_b128 v[146:149], v24 offset:19456
	ds_read_b128 v[158:161], v24 offset:18432
	ds_read_b128 v[162:165], v24 offset:17408
	ds_read_b128 v[226:229], v24 offset:16384
	s_setprio 1
	s_waitcnt lgkmcnt(0)
	v_mfma_f32_16x16x32_bf16 v[124:127], v[226:229], v[20:23], v[124:127]
	v_mfma_f32_16x16x32_bf16 v[64:67], v[162:165], v[20:23], v[120:123]
	v_mfma_f32_16x16x32_bf16 v[32:35], v[158:161], v[20:23], v[116:119]
	v_mfma_f32_16x16x32_bf16 v[28:31], v[146:149], v[20:23], v[112:115]
	v_mfma_f32_16x16x32_bf16 v[120:123], v[226:229], v[16:19], v[108:111]
	v_mfma_f32_16x16x32_bf16 v[68:71], v[162:165], v[16:19], v[96:99]
	v_mfma_f32_16x16x32_bf16 v[36:39], v[158:161], v[16:19], v[84:87]
	v_mfma_f32_16x16x32_bf16 v[24:27], v[146:149], v[16:19], v[80:83]
	v_mfma_f32_16x16x32_bf16 v[116:119], v[226:229], v[12:15], v[76:79]
	v_mfma_f32_16x16x32_bf16 v[72:75], v[162:165], v[12:15], v[72:75]
	v_mfma_f32_16x16x32_bf16 v[40:43], v[158:161], v[12:15], v[150:153]
	v_mfma_f32_16x16x32_bf16 v[20:23], v[146:149], v[12:15], v[154:157]
	v_mfma_f32_16x16x32_bf16 v[108:111], v[226:229], v[8:11], v[60:63]
	v_mfma_f32_16x16x32_bf16 v[76:79], v[162:165], v[8:11], v[56:59]
	v_mfma_f32_16x16x32_bf16 v[44:47], v[158:161], v[8:11], v[52:55]
	v_mfma_f32_16x16x32_bf16 v[12:15], v[146:149], v[8:11], v[48:51]
	s_setprio 0
	ds_read_b128 v[8:11], v88 offset:4096
	ds_read_b128 v[56:59], v88 offset:5120
	ds_read_b128 v[60:63], v88 offset:6144
	ds_read_b128 v[150:153], v88 offset:7168
	s_setprio 1
	s_waitcnt lgkmcnt(3)
	v_mfma_f32_16x16x32_bf16 v[112:115], v[226:229], v[8:11], v[166:169]
	v_mfma_f32_16x16x32_bf16 v[80:83], v[162:165], v[8:11], v[186:189]
	v_mfma_f32_16x16x32_bf16 v[48:51], v[158:161], v[8:11], v[190:193]
	v_mfma_f32_16x16x32_bf16 v[16:19], v[146:149], v[8:11], v[194:197]
	s_waitcnt lgkmcnt(2)
	v_mfma_f32_16x16x32_bf16 v[104:107], v[226:229], v[56:59], v[198:201]
	v_mfma_f32_16x16x32_bf16 v[84:87], v[162:165], v[56:59], v[202:205]
	v_mfma_f32_16x16x32_bf16 v[52:55], v[158:161], v[56:59], v[206:209]
	v_mfma_f32_16x16x32_bf16 v[8:11], v[146:149], v[56:59], v[210:213]
	s_waitcnt lgkmcnt(1)
; DEVI int opaque_tid() { int t = (int)threadIdx.x; asm volatile("" : "+v"(t)); return t; }
; DEVI void g2_issue(const G2Tile& t, int kt, int st, char* smem) {
;     const int tid = opaque_tid(), lane = tid & 63, w = tid >> 6;
;     const int rr = lane >> 2, sch = (lane & 3) ^ ((lane >> 5) << 1);
;     const bf16_t* ap = t.A + (size_t)kt * 32 + (size_t)(w * 16 + rr) * t.lda + sch * 8;
;     const bf16_t* bp = t.Bt + (size_t)kt * 32 + (size_t)(w * 16 + rr) * t.ldb + sch * 8;
;     char* sa = smem + st * 24576 + w * 1024 + lane * 16;
; #pragma unroll
;     for (int i = 0; i < 4; ++i) __builtin_amdgcn_global_load_lds((const unsigned*)(ap + (size_t)(64 * i) * t.lda), (unsigned*)(sa + i * 4096), 16, 0, 0);
; #pragma unroll
;     for (int i = 0; i < 2; ++i) __builtin_amdgcn_global_load_lds((const unsigned*)(bp + (size_t)(64 * i) * t.ldb), (unsigned*)(sa + 16384 + i * 4096), 16, 0, 0);
; }
; DEVI void g2_prologue(const G2Tile& t, int st, char* smem) {
;     g2_issue(t, 0, st, smem);
;     g2_issue(t, 1, st == 2 ? 0 : st + 1, smem);
;     template <int MT> DEVI void operator()(f32x4 (&acc)[MT][4], int row0, int col0, int fr, int fq) const {
; #pragma unroll
;         for (int n = 0; n < 4; ++n) {
;             const int e = col0 + 16 * n + 4 * fq;
;             f32x4 pv = *(const f32x4*)(ps1024 + b * 1024 + e);
;             if (par) pv = (f32x4){0.f, 0.f, 0.f, 0.f};
	v_mfma_f32_16x16x32_bf16 v[100:103], v[226:229], v[60:63], v[218:221]
	v_mfma_f32_16x16x32_bf16 v[88:91], v[162:165], v[60:63], v[222:225]
	v_mfma_f32_16x16x32_bf16 v[56:59], v[158:161], v[60:63], v[4:7]
	v_mfma_f32_16x16x32_bf16 v[4:7], v[146:149], v[60:63], v[0:3]
	s_waitcnt lgkmcnt(0)
	v_mfma_f32_16x16x32_bf16 v[96:99], v[226:229], v[150:153], v[134:137]
	v_mfma_f32_16x16x32_bf16 v[92:95], v[162:165], v[150:153], v[92:95]
	v_mfma_f32_16x16x32_bf16 v[60:63], v[158:161], v[150:153], v[138:141]
	v_mfma_f32_16x16x32_bf16 v[0:3], v[146:149], v[150:153], v[142:145]
	s_setprio 0
	s_add_i32 s44, s26, 1
	v_mov_b32_e32 v131, v172
	s_cmp_lg_u32 s26, 2
	s_cselect_b32 s72, s44, 0
	v_and_b32_e32 v136, 63, v131
	v_ashrrev_i32_e32 v137, 6, v131
	v_bfe_u32 v132, v131, 2, 4
	v_and_b32_e32 v133, 3, v131
	v_lshrrev_b32_e32 v131, 4, v131
	v_bitop3_b32 v131, v131, v133, 2 bitop3:0x6c
	v_lshl_or_b32 v132, v137, 4, v132
	s_mul_i32 s44, s72, 0x6000
	v_ashrrev_i32_e32 v133, 31, v132
	v_lshlrev_b32_e32 v184, 4, v131
	s_add_i32 s45, s44, 0
	v_lshlrev_b32_e32 v131, 10, v137
	v_lshlrev_b32_e32 v136, 4, v136
	v_lshlrev_b64 v[132:133], 11, v[132:133]
	v_add3_u32 v131, s45, v131, v136
	v_lshl_add_u64 v[134:135], s[34:35], 0, v[132:133]
	v_readfirstlane_b32 s45, v131
	v_add_u32_e32 v138, 0x1000, v131
	v_lshl_add_u64 v[134:135], v[134:135], 0, v[184:185]
	s_mov_b32 m0, s45
	v_readfirstlane_b32 s45, v138
	v_add_u32_e32 v138, 0x2000, v131
	global_load_lds_dwordx4 v[134:135], off
	v_lshl_add_u64 v[136:137], v[134:135], 0, s[6:7]
	s_mov_b32 m0, s45
	v_readfirstlane_b32 s45, v138
	global_load_lds_dwordx4 v[136:137], off
	v_lshl_add_u64 v[136:137], v[134:135], 0, s[8:9]
	s_mov_b32 m0, s45
	v_lshl_add_u64 v[134:135], v[134:135], 0, s[10:11]
	global_load_lds_dwordx4 v[136:137], off
	v_add_u32_e32 v136, 0x3000, v131
	v_lshl_add_u64 v[132:133], s[36:37], 0, v[132:133]
	v_readfirstlane_b32 s45, v136
	s_mov_b32 m0, s45
	v_lshl_add_u64 v[132:133], v[132:133], 0, v[184:185]
	global_load_lds_dwordx4 v[134:135], off
	v_add_u32_e32 v134, 0x4000, v131
	v_add_u32_e32 v131, 0x5000, v131
	v_readfirstlane_b32 s45, v134
	s_mov_b32 m0, s45
	v_readfirstlane_b32 s45, v131
	global_load_lds_dwordx4 v[132:133], off
	v_lshl_add_u64 v[132:133], v[132:133], 0, s[6:7]
	s_mov_b32 m0, s45
	v_mov_b32_e32 v131, v172
	global_load_lds_dwordx4 v[132:133], off
	s_and_b32 s26, s79, 1
	v_ashrrev_i32_e32 v139, 6, v131
	v_bfe_u32 v132, v131, 2, 4
	v_and_b32_e32 v138, 63, v131
	v_and_b32_e32 v133, 3, v131
	v_lshrrev_b32_e32 v131, 4, v131
	v_lshl_or_b32 v132, v139, 4, v132
	v_bitop3_b32 v131, v131, v133, 2 bitop3:0x6c
	v_ashrrev_i32_e32 v133, 31, v132
	s_addk_i32 s44, 0x6000
	v_lshlrev_b64 v[132:133], 11, v[132:133]
	s_cmp_lg_u32 s72, 2
	v_lshl_add_u64 v[134:135], s[34:35], 0, v[132:133]
	s_cselect_b32 s34, s44, 0
	v_lshlrev_b32_e32 v184, 4, v131
	s_add_i32 s34, s34, 0
	v_lshlrev_b32_e32 v131, 10, v139
	v_lshlrev_b32_e32 v138, 4, v138
	v_add3_u32 v131, s34, v131, v138
	v_lshl_add_u64 v[134:135], v[134:135], 0, v[184:185]
	v_readfirstlane_b32 s34, v131
	v_add_u32_e32 v138, 0x1000, v131
	v_lshl_add_u64 v[136:137], v[134:135], 0, 64
	s_mov_b32 m0, s34
	v_readfirstlane_b32 s34, v138
	v_add_u32_e32 v138, 0x2000, v131
	global_load_lds_dwordx4 v[136:137], off
	v_lshl_add_u64 v[136:137], v[134:135], 0, s[12:13]
	s_mov_b32 m0, s34
	v_readfirstlane_b32 s34, v138
	global_load_lds_dwordx4 v[136:137], off
	v_lshl_add_u64 v[136:137], v[134:135], 0, s[14:15]
	s_mov_b32 m0, s34
	v_lshl_add_u64 v[132:133], s[36:37], 0, v[132:133]
	global_load_lds_dwordx4 v[136:137], off
	v_add_u32_e32 v136, 0x3000, v131
	v_lshl_add_u64 v[134:135], v[134:135], 0, s[16:17]
	v_readfirstlane_b32 s34, v136
	v_add_u32_e32 v136, 0x4000, v131
	s_mov_b32 m0, s34
	v_lshl_add_u64 v[132:133], v[132:133], 0, v[184:185]
	v_readfirstlane_b32 s34, v136
	v_add_u32_e32 v131, 0x5000, v131
	global_load_lds_dwordx4 v[134:135], off
	v_lshl_add_u64 v[134:135], v[132:133], 0, 64
	s_mov_b32 m0, s34
	v_readfirstlane_b32 s34, v131
	global_load_lds_dwordx4 v[134:135], off
	s_mov_b32 m0, s34
	s_lshl_b32 s34, s33, 10
	v_lshlrev_b32_e32 v129, 6, v129
	v_lshlrev_b32_e32 v130, 2, v130
	s_ashr_i32 s35, s34, 31
	v_add3_u32 v130, v129, s77, v130
	s_lshl_b64 s[34:35], s[34:35], 2
	s_add_u32 s34, s59, s34
	v_ashrrev_i32_e32 v131, 31, v130
	s_addc_u32 s35, s60, s35
	v_lshlrev_b64 v[136:137], 2, v[130:131]
	v_lshl_add_u64 v[132:133], v[132:133], 0, s[12:13]
	v_lshl_add_u64 v[130:131], s[34:35], 0, v[136:137]
	global_load_lds_dwordx4 v[132:133], off
	global_load_dwordx4 v[132:135], v[130:131], off
	v_and_b32_e32 v128, 0xffffff8f, v128
	v_add_u32_e32 v129, s78, v128
	v_and_b32_e32 v128, 1, v129
	v_cmp_eq_u32_e32 vcc, 0, v128
	s_cmp_eq_u32 s26, 0
	s_mov_b64 s[36:37], 0
	v_cndmask_b32_e64 v128, -1.0, 1.0, vcc
	s_cselect_b64 vcc, -1, 0
	s_lshl_b32 s33, s33, 11
	s_lshl_b32 s26, s26, 10
	s_or_b32 s26, s26, s33
	s_or_b32 s34, s28, s75
	s_ashr_i32 s35, s34, 31
	s_lshl_b64 s[34:35], s[34:35], 11
	s_waitcnt vmcnt(0)
;     template <int MT> DEVI void operator()(f32x4 (&acc)[MT][4], int row0, int col0, int fr, int fq) const {
; #pragma unroll
;         for (int n = 0; n < 4; ++n) {
;             const int e = col0 + 16 * n + 4 * fq;
;             f32x4 pv = *(const f32x4*)(ps1024 + b * 1024 + e);
;             if (par) pv = (f32x4){0.f, 0.f, 0.f, 0.f};
; #pragma unroll
;             for (int m = 0; m < MT; ++m) {
;                 const int k = row0 + 16 * m + fr;
;                 const float sg = (k & 1) ? -1.0f : 1.0f;
;                 *(f32x4*)(T + ((size_t)((b * 2 + par) * 1024 + k)) * 1024 + e) = acc[m][n] + pv * sg;
;             }
;         }
	v_cndmask_b32_e32 v141, 0, v135, vcc
	v_cndmask_b32_e32 v140, 0, v134, vcc
	v_pk_fma_f32 v[134:135], v[128:129], v[140:141], v[126:127] op_sel_hi:[0,1,1]
	v_add_u32_e32 v126, s26, v129
	v_cndmask_b32_e32 v139, 0, v133, vcc
	v_cndmask_b32_e32 v138, 0, v132, vcc
	v_ashrrev_i32_e32 v127, 31, v126
	v_pk_fma_f32 v[132:133], v[128:129], v[138:139], v[124:125] op_sel_hi:[0,1,1]
	v_lshlrev_b64 v[124:125], 12, v[126:127]
	v_lshl_add_u64 v[124:125], s[40:41], 0, v[124:125]
	v_lshl_add_u64 v[124:125], v[124:125], 0, v[136:137]
	global_store_dwordx4 v[124:125], v[132:135], off
	v_pk_fma_f32 v[114:115], v[128:129], v[140:141], v[114:115] op_sel_hi:[0,1,1]
	v_pk_fma_f32 v[112:113], v[128:129], v[138:139], v[112:113] op_sel_hi:[0,1,1]
	v_pk_fma_f32 v[132:133], v[128:129], v[138:139], v[120:121] op_sel_hi:[0,1,1]
	v_add_u32_e32 v120, 16, v126
	v_ashrrev_i32_e32 v121, 31, v120
	v_lshlrev_b64 v[120:121], 12, v[120:121]
	v_lshl_add_u64 v[120:121], s[40:41], 0, v[120:121]
	v_pk_fma_f32 v[134:135], v[128:129], v[140:141], v[122:123] op_sel_hi:[0,1,1]
	v_lshl_add_u64 v[120:121], v[120:121], 0, v[136:137]
	global_store_dwordx4 v[120:121], v[132:135], off
	s_add_u32 s26, s76, s34
	s_addc_u32 s33, 0, s35
	v_pk_fma_f32 v[132:133], v[128:129], v[138:139], v[116:117] op_sel_hi:[0,1,1]
	v_add_u32_e32 v116, 32, v126
	v_ashrrev_i32_e32 v117, 31, v116
	v_lshlrev_b64 v[116:117], 12, v[116:117]
	v_lshl_add_u64 v[116:117], s[40:41], 0, v[116:117]
	v_pk_fma_f32 v[134:135], v[128:129], v[140:141], v[118:119] op_sel_hi:[0,1,1]
	v_lshl_add_u64 v[116:117], v[116:117], 0, v[136:137]
	global_store_dwordx4 v[116:117], v[132:135], off
	s_add_u32 s34, s90, s26
	s_addc_u32 s35, s91, s33
	v_pk_fma_f32 v[132:133], v[128:129], v[138:139], v[108:109] op_sel_hi:[0,1,1]
	v_add_u32_e32 v108, 48, v126
	v_ashrrev_i32_e32 v109, 31, v108
	v_lshlrev_b64 v[108:109], 12, v[108:109]
	v_lshl_add_u64 v[108:109], s[40:41], 0, v[108:109]
	v_pk_fma_f32 v[134:135], v[128:129], v[140:141], v[110:111] op_sel_hi:[0,1,1]
	v_lshl_add_u64 v[110:111], v[108:109], 0, v[136:137]
	v_add_u32_e32 v108, 64, v126
	v_ashrrev_i32_e32 v109, 31, v108
	v_lshlrev_b64 v[108:109], 12, v[108:109]
	v_lshl_add_u64 v[108:109], s[40:41], 0, v[108:109]
	v_lshl_add_u64 v[108:109], v[108:109], 0, v[136:137]
	global_store_dwordx4 v[108:109], v[112:115], off
	global_store_dwordx4 v[110:111], v[132:135], off
	s_nop 0
	v_pk_fma_f32 v[112:113], v[128:129], v[138:139], v[104:105] op_sel_hi:[0,1,1]
	v_add_u32_e32 v104, 0x50, v126
	v_ashrrev_i32_e32 v105, 31, v104
	v_lshlrev_b64 v[104:105], 12, v[104:105]
	v_lshl_add_u64 v[104:105], s[40:41], 0, v[104:105]
	v_pk_fma_f32 v[114:115], v[128:129], v[140:141], v[106:107] op_sel_hi:[0,1,1]
	v_lshl_add_u64 v[104:105], v[104:105], 0, v[136:137]
	global_store_dwordx4 v[104:105], v[112:115], off
	s_nop 1
	v_pk_fma_f32 v[112:113], v[128:129], v[138:139], v[100:101] op_sel_hi:[0,1,1]
	v_add_u32_e32 v100, 0x60, v126
	v_ashrrev_i32_e32 v101, 31, v100
	v_lshlrev_b64 v[100:101], 12, v[100:101]
	v_lshl_add_u64 v[100:101], s[40:41], 0, v[100:101]
	v_pk_fma_f32 v[114:115], v[128:129], v[140:141], v[102:103] op_sel_hi:[0,1,1]
	v_lshl_add_u64 v[100:101], v[100:101], 0, v[136:137]
	global_store_dwordx4 v[100:101], v[112:115], off
	s_nop 1
	v_pk_fma_f32 v[112:113], v[128:129], v[138:139], v[96:97] op_sel_hi:[0,1,1]
	v_add_u32_e32 v96, 0x70, v126
	v_ashrrev_i32_e32 v97, 31, v96
	v_lshlrev_b64 v[96:97], 12, v[96:97]
	v_lshl_add_u64 v[96:97], s[40:41], 0, v[96:97]
	v_pk_fma_f32 v[114:115], v[128:129], v[140:141], v[98:99] op_sel_hi:[0,1,1]
	v_lshl_add_u64 v[96:97], v[96:97], 0, v[136:137]
	global_store_dwordx4 v[96:97], v[112:115], off
	global_load_dwordx4 v[112:115], v[130:131], off offset:64
	v_mov_b32_e32 v136, v172
	s_waitcnt vmcnt(0)
	v_cndmask_b32_e32 v99, 0, v113, vcc
	v_cndmask_b32_e32 v98, 0, v112, vcc
	v_cndmask_b32_e32 v103, 0, v115, vcc
	v_cndmask_b32_e32 v102, 0, v114, vcc
	v_pk_fma_f32 v[66:67], v[128:129], v[102:103], v[66:67] op_sel_hi:[0,1,1]
	v_pk_fma_f32 v[64:65], v[128:129], v[98:99], v[64:65] op_sel_hi:[0,1,1]
	global_store_dwordx4 v[124:125], v[64:67], off offset:64
	s_nop 1
	v_pk_fma_f32 v[66:67], v[128:129], v[102:103], v[70:71] op_sel_hi:[0,1,1]
	v_pk_fma_f32 v[64:65], v[128:129], v[98:99], v[68:69] op_sel_hi:[0,1,1]
	global_store_dwordx4 v[120:121], v[64:67], off offset:64
	s_nop 1
	v_pk_fma_f32 v[66:67], v[128:129], v[102:103], v[74:75] op_sel_hi:[0,1,1]
	v_pk_fma_f32 v[64:65], v[128:129], v[98:99], v[72:73] op_sel_hi:[0,1,1]
	global_store_dwordx4 v[116:117], v[64:67], off offset:64
	s_nop 1
	v_pk_fma_f32 v[66:67], v[128:129], v[102:103], v[78:79] op_sel_hi:[0,1,1]
	v_pk_fma_f32 v[64:65], v[128:129], v[98:99], v[76:77] op_sel_hi:[0,1,1]
	global_store_dwordx4 v[110:111], v[64:67], off offset:64
	s_nop 1
	v_pk_fma_f32 v[66:67], v[128:129], v[102:103], v[82:83] op_sel_hi:[0,1,1]
	v_pk_fma_f32 v[64:65], v[128:129], v[98:99], v[80:81] op_sel_hi:[0,1,1]
	global_store_dwordx4 v[108:109], v[64:67], off offset:64
	s_nop 1
	v_pk_fma_f32 v[66:67], v[128:129], v[102:103], v[86:87] op_sel_hi:[0,1,1]
	v_pk_fma_f32 v[64:65], v[128:129], v[98:99], v[84:85] op_sel_hi:[0,1,1]
	global_store_dwordx4 v[104:105], v[64:67], off offset:64
	s_nop 1
	v_pk_fma_f32 v[66:67], v[128:129], v[102:103], v[90:91] op_sel_hi:[0,1,1]
	v_pk_fma_f32 v[64:65], v[128:129], v[98:99], v[88:89] op_sel_hi:[0,1,1]
	global_store_dwordx4 v[100:101], v[64:67], off offset:64
	s_nop 1
	v_pk_fma_f32 v[66:67], v[128:129], v[102:103], v[94:95] op_sel_hi:[0,1,1]
	v_pk_fma_f32 v[64:65], v[128:129], v[98:99], v[92:93] op_sel_hi:[0,1,1]
	global_store_dwordx4 v[96:97], v[64:67], off offset:64
	global_load_dwordx4 v[64:67], v[130:131], off offset:128
	s_waitcnt vmcnt(0)
; DEVI int opaque_tid() { int t = (int)threadIdx.x; asm volatile("" : "+v"(t)); return t; }
; template <bool TRANS, class Epi>
; DEVI int g2_body(const G2Tile& t, int st, char* smem, bool has_next, const G2Tile& nxt, const Epi& epi) {
;     const int tid = opaque_tid(), lane = tid & 63, w = tid >> 6, wr = w >> 1, wc = w & 1, fr = lane & 15, fq = lane >> 4;
;     f32x4 acc[8][4];
; #pragma unroll
;     for (int m = 0; m < 8; ++m)
; #pragma unroll
;         for (int n = 0; n < 4; ++n) acc[m][n] = (f32x4){0.f, 0.f, 0.f, 0.f};
;     const int frag = fr * 64 + ((fq ^ ((fr >> 3) << 1)) << 4);
;     template <int MT> DEVI void operator()(f32x4 (&acc)[MT][4], int row0, int col0, int fr, int fq) const {
; #pragma unroll
;         for (int n = 0; n < 4; ++n) {
;             const int e = col0 + 16 * n + 4 * fq;
;             f32x4 pv = *(const f32x4*)(ps1024 + b * 1024 + e);
;             if (par) pv = (f32x4){0.f, 0.f, 0.f, 0.f};
; #pragma unroll
;             for (int m = 0; m < MT; ++m) {
;                 const int k = row0 + 16 * m + fr;
;                 const float sg = (k & 1) ? -1.0f : 1.0f;
;                 *(f32x4*)(T + ((size_t)((b * 2 + par) * 1024 + k)) * 1024 + e) = acc[m][n] + pv * sg;
;             }
;         }
	v_cndmask_b32_e32 v65, 0, v65, vcc
	v_cndmask_b32_e32 v64, 0, v64, vcc
	v_cndmask_b32_e32 v67, 0, v67, vcc
	v_cndmask_b32_e32 v66, 0, v66, vcc
	v_pk_fma_f32 v[34:35], v[128:129], v[66:67], v[34:35] op_sel_hi:[0,1,1]
	v_pk_fma_f32 v[32:33], v[128:129], v[64:65], v[32:33] op_sel_hi:[0,1,1]
	global_store_dwordx4 v[124:125], v[32:35], off offset:128
	s_nop 1
	v_pk_fma_f32 v[34:35], v[128:129], v[66:67], v[38:39] op_sel_hi:[0,1,1]
	v_pk_fma_f32 v[32:33], v[128:129], v[64:65], v[36:37] op_sel_hi:[0,1,1]
	global_store_dwordx4 v[120:121], v[32:35], off offset:128
	s_nop 1
	v_pk_fma_f32 v[34:35], v[128:129], v[66:67], v[42:43] op_sel_hi:[0,1,1]
	v_pk_fma_f32 v[32:33], v[128:129], v[64:65], v[40:41] op_sel_hi:[0,1,1]
	global_store_dwordx4 v[116:117], v[32:35], off offset:128
	s_nop 1
	v_pk_fma_f32 v[34:35], v[128:129], v[66:67], v[46:47] op_sel_hi:[0,1,1]
	v_pk_fma_f32 v[32:33], v[128:129], v[64:65], v[44:45] op_sel_hi:[0,1,1]
	global_store_dwordx4 v[110:111], v[32:35], off offset:128
	s_nop 1
	v_pk_fma_f32 v[34:35], v[128:129], v[66:67], v[50:51] op_sel_hi:[0,1,1]
	v_pk_fma_f32 v[32:33], v[128:129], v[64:65], v[48:49] op_sel_hi:[0,1,1]
	global_store_dwordx4 v[108:109], v[32:35], off offset:128
	s_nop 1
	v_pk_fma_f32 v[34:35], v[128:129], v[66:67], v[54:55] op_sel_hi:[0,1,1]
	v_pk_fma_f32 v[32:33], v[128:129], v[64:65], v[52:53] op_sel_hi:[0,1,1]
	global_store_dwordx4 v[104:105], v[32:35], off offset:128
	s_nop 1
	v_pk_fma_f32 v[34:35], v[128:129], v[66:67], v[58:59] op_sel_hi:[0,1,1]
	v_pk_fma_f32 v[32:33], v[128:129], v[64:65], v[56:57] op_sel_hi:[0,1,1]
	global_store_dwordx4 v[100:101], v[32:35], off offset:128
	s_nop 1
	v_pk_fma_f32 v[34:35], v[128:129], v[66:67], v[62:63] op_sel_hi:[0,1,1]
	v_pk_fma_f32 v[32:33], v[128:129], v[64:65], v[60:61] op_sel_hi:[0,1,1]
	global_store_dwordx4 v[96:97], v[32:35], off offset:128
	global_load_dwordx4 v[32:35], v[130:131], off offset:192
	s_waitcnt vmcnt(0)
	v_cndmask_b32_e32 v33, 0, v33, vcc
	v_cndmask_b32_e32 v32, 0, v32, vcc
	v_cndmask_b32_e32 v35, 0, v35, vcc
	v_cndmask_b32_e32 v34, 0, v34, vcc
	v_pk_fma_f32 v[14:15], v[128:129], v[34:35], v[14:15] op_sel_hi:[0,1,1]
	v_pk_fma_f32 v[12:13], v[128:129], v[32:33], v[12:13] op_sel_hi:[0,1,1]
	v_pk_fma_f32 v[30:31], v[128:129], v[34:35], v[30:31] op_sel_hi:[0,1,1]
	v_pk_fma_f32 v[28:29], v[128:129], v[32:33], v[28:29] op_sel_hi:[0,1,1]
	v_pk_fma_f32 v[26:27], v[128:129], v[34:35], v[26:27] op_sel_hi:[0,1,1]
	v_pk_fma_f32 v[24:25], v[128:129], v[32:33], v[24:25] op_sel_hi:[0,1,1]
	v_pk_fma_f32 v[22:23], v[128:129], v[34:35], v[22:23] op_sel_hi:[0,1,1]
	v_pk_fma_f32 v[20:21], v[128:129], v[32:33], v[20:21] op_sel_hi:[0,1,1]
	global_store_dwordx4 v[110:111], v[12:15], off offset:192
	v_pk_fma_f32 v[10:11], v[128:129], v[34:35], v[10:11] op_sel_hi:[0,1,1]
	v_pk_fma_f32 v[8:9], v[128:129], v[32:33], v[8:9] op_sel_hi:[0,1,1]
	v_pk_fma_f32 v[14:15], v[128:129], v[34:35], v[18:19] op_sel_hi:[0,1,1]
	v_pk_fma_f32 v[12:13], v[128:129], v[32:33], v[16:17] op_sel_hi:[0,1,1]
	v_pk_fma_f32 v[6:7], v[128:129], v[34:35], v[6:7] op_sel_hi:[0,1,1]
	v_pk_fma_f32 v[4:5], v[128:129], v[32:33], v[4:5] op_sel_hi:[0,1,1]
	v_pk_fma_f32 v[2:3], v[128:129], v[34:35], v[2:3] op_sel_hi:[0,1,1]
	v_pk_fma_f32 v[0:1], v[128:129], v[32:33], v[0:1] op_sel_hi:[0,1,1]
	global_store_dwordx4 v[124:125], v[28:31], off offset:192
	global_store_dwordx4 v[120:121], v[24:27], off offset:192
	global_store_dwordx4 v[116:117], v[20:23], off offset:192
	global_store_dwordx4 v[108:109], v[12:15], off offset:192
	global_store_dwordx4 v[104:105], v[8:11], off offset:192
	global_store_dwordx4 v[100:101], v[4:7], off offset:192
	global_store_dwordx4 v[96:97], v[0:3], off offset:192
	s_nop 0
	v_and_b32_e32 v137, 15, v136
	v_lshrrev_b32_e32 v2, 2, v136
	v_lshrrev_b32_e32 v0, 4, v136
	v_and_b32_e32 v2, 2, v2
	v_bitop3_b32 v0, v0, v2, 3 bitop3:0x6c
	v_lshlrev_b32_e32 v1, 6, v137
	v_lshlrev_b32_e32 v0, 4, v0
	v_add3_u32 v129, 0, v1, v0
	v_lshlrev_b32_e32 v0, 6, v136
	v_bfe_u32 v138, v136, 6, 1
	v_and_b32_e32 v130, 0xffffe000, v0
	v_mov_b32_e32 v0, 0
	v_bfe_u32 v177, v136, 4, 2
	v_lshlrev_b32_e32 v128, 12, v138
	v_mov_b32_e32 v1, v0
	v_mov_b32_e32 v2, v0
	v_mov_b32_e32 v3, v0
	v_mov_b32_e32 v4, v0
	v_mov_b32_e32 v5, v0
	v_mov_b32_e32 v6, v0
	v_mov_b32_e32 v7, v0
	v_mov_b32_e32 v8, v0
	v_mov_b32_e32 v9, v0
	v_mov_b32_e32 v10, v0
	v_mov_b32_e32 v11, v0
	v_mov_b32_e32 v12, v0
	v_mov_b32_e32 v13, v0
	v_mov_b32_e32 v14, v0
	v_mov_b32_e32 v15, v0
	v_mov_b32_e32 v16, v0
	v_mov_b32_e32 v17, v0
	v_mov_b32_e32 v18, v0
	v_mov_b32_e32 v19, v0
	v_mov_b32_e32 v20, v0
	v_mov_b32_e32 v21, v0
	v_mov_b32_e32 v22, v0
	v_mov_b32_e32 v23, v0
	v_mov_b32_e32 v24, v0
	v_mov_b32_e32 v25, v0
	v_mov_b32_e32 v26, v0
	v_mov_b32_e32 v27, v0
	v_mov_b32_e32 v28, v0
	v_mov_b32_e32 v29, v0
	v_mov_b32_e32 v30, v0
	v_mov_b32_e32 v31, v0
	v_mov_b32_e32 v32, v0
	v_mov_b32_e32 v33, v0
	v_mov_b32_e32 v34, v0
	v_mov_b32_e32 v35, v0
	v_mov_b32_e32 v36, v0
	v_mov_b32_e32 v37, v0
	v_mov_b32_e32 v38, v0
	v_mov_b32_e32 v39, v0
	v_mov_b32_e32 v40, v0
	v_mov_b32_e32 v41, v0
	v_mov_b32_e32 v42, v0
	v_mov_b32_e32 v43, v0
	v_mov_b32_e32 v44, v0
	v_mov_b32_e32 v45, v0
	v_mov_b32_e32 v46, v0
	v_mov_b32_e32 v47, v0
	v_mov_b32_e32 v48, v0
	v_mov_b32_e32 v49, v0
	v_mov_b32_e32 v50, v0
	v_mov_b32_e32 v51, v0
	v_mov_b32_e32 v52, v0
	v_mov_b32_e32 v53, v0
	v_mov_b32_e32 v54, v0
	v_mov_b32_e32 v55, v0
	v_mov_b32_e32 v56, v0
	v_mov_b32_e32 v57, v0
	v_mov_b32_e32 v58, v0
	v_mov_b32_e32 v59, v0
	v_mov_b32_e32 v60, v0
	v_mov_b32_e32 v61, v0
	v_mov_b32_e32 v62, v0
	v_mov_b32_e32 v63, v0
	v_mov_b32_e32 v64, v0
	v_mov_b32_e32 v65, v0
	v_mov_b32_e32 v66, v0
	v_mov_b32_e32 v67, v0
; DEVI void g2_issue(const G2Tile& t, int kt, int st, char* smem) {
;     const int tid = opaque_tid(), lane = tid & 63, w = tid >> 6;
;     const int rr = lane >> 2, sch = (lane & 3) ^ ((lane >> 5) << 1);
;     const bf16_t* ap = t.A + (size_t)kt * 32 + (size_t)(w * 16 + rr) * t.lda + sch * 8;
;     const bf16_t* bp = t.Bt + (size_t)kt * 32 + (size_t)(w * 16 + rr) * t.ldb + sch * 8;
;     char* sa = smem + st * 24576 + w * 1024 + lane * 16;
; #pragma unroll
;     for (int i = 0; i < 4; ++i) __builtin_amdgcn_global_load_lds((const unsigned*)(ap + (size_t)(64 * i) * t.lda), (unsigned*)(sa + i * 4096), 16, 0, 0);
; #pragma unroll
; template <bool TRANS, class Epi>
; DEVI int g2_body(const G2Tile& t, int st, char* smem, bool has_next, const G2Tile& nxt, const Epi& epi) {
;     const int tid = opaque_tid(), lane = tid & 63, w = tid >> 6, wr = w >> 1, wc = w & 1, fr = lane & 15, fq = lane >> 4;
;     f32x4 acc[8][4];
; #pragma unroll
;     for (int m = 0; m < 8; ++m)
; #pragma unroll
;         for (int n = 0; n < 4; ++n) acc[m][n] = (f32x4){0.f, 0.f, 0.f, 0.f};
;     const int frag = fr * 64 + ((fq ^ ((fr >> 3) << 1)) << 4);
;     const int nk = t.nk;
;     for (int kt = 0; kt < nk; ++kt) {
;         if (kt + 1 < nk) asm volatile("s_waitcnt vmcnt(6)" ::: "memory");
;         else asm volatile("s_waitcnt vmcnt(0)" ::: "memory");
;         __syncthreads();
;         if (kt + 2 < nk) g2_issue(t, kt + 2, st >= 1 ? st - 1 : 2, smem);
;         const char* sa = smem + st * 24576 + frag;
;         bf16x8 bfr[4];
; #pragma unroll
;         for (int n = 0; n < 4; ++n) bfr[n] = *(const bf16x8*)(sa + (16 + wc * 4 + n) * 1024);
; #pragma unroll
;         for (int mh = 0; mh < 2; ++mh) {
;             bf16x8 af[4];
; #pragma unroll
;             for (int m = 0; m < 4; ++m) af[m] = *(const bf16x8*)(sa + (wr * 8 + mh * 4 + m) * 1024);
;             __builtin_amdgcn_s_setprio(1);
; #pragma unroll
;             for (int m = 0; m < 4; ++m)
; #pragma unroll
;                 for (int n = 0; n < 4; ++n)
;                     acc[mh * 4 + m][n] = TRANS ? __builtin_amdgcn_mfma_f32_16x16x32_bf16(bfr[n], af[m], acc[mh * 4 + m][n], 0, 0, 0)
;                                                : __builtin_amdgcn_mfma_f32_16x16x32_bf16(af[m], bfr[n], acc[mh * 4 + m][n], 0, 0, 0);
;             __builtin_amdgcn_s_setprio(0);
;         }
;         st = st == 2 ? 0 : st + 1;
;     }
	v_mov_b32_e32 v68, v0
	v_mov_b32_e32 v69, v0
	v_mov_b32_e32 v70, v0
	v_mov_b32_e32 v71, v0
	v_mov_b32_e32 v72, v0
	v_mov_b32_e32 v73, v0
	v_mov_b32_e32 v74, v0
	v_mov_b32_e32 v75, v0
	v_mov_b32_e32 v76, v0
	v_mov_b32_e32 v77, v0
	v_mov_b32_e32 v78, v0
	v_mov_b32_e32 v79, v0
	v_mov_b32_e32 v80, v0
	v_mov_b32_e32 v81, v0
	v_mov_b32_e32 v82, v0
	v_mov_b32_e32 v83, v0
	v_mov_b32_e32 v84, v0
	v_mov_b32_e32 v85, v0
	v_mov_b32_e32 v86, v0
	v_mov_b32_e32 v87, v0
	v_mov_b32_e32 v96, v0
	v_mov_b32_e32 v97, v0
	v_mov_b32_e32 v98, v0
	v_mov_b32_e32 v99, v0
	v_mov_b32_e32 v108, v0
	v_mov_b32_e32 v109, v0
	v_mov_b32_e32 v110, v0
	v_mov_b32_e32 v111, v0
	v_mov_b32_e32 v112, v0
	v_mov_b32_e32 v113, v0
	v_mov_b32_e32 v114, v0
	v_mov_b32_e32 v115, v0
	v_mov_b32_e32 v116, v0
	v_mov_b32_e32 v117, v0
	v_mov_b32_e32 v118, v0
	v_mov_b32_e32 v119, v0
	v_mov_b32_e32 v120, v0
	v_mov_b32_e32 v121, v0
	v_mov_b32_e32 v122, v0
	v_mov_b32_e32 v123, v0
	v_mov_b32_e32 v124, v0
	v_mov_b32_e32 v125, v0
	v_mov_b32_e32 v126, v0
	v_mov_b32_e32 v127, v0
	v_mov_b32_e32 v88, v0
	v_mov_b32_e32 v89, v0
	v_mov_b32_e32 v90, v0
	v_mov_b32_e32 v91, v0
	v_mov_b32_e32 v92, v0
	v_mov_b32_e32 v93, v0
	v_mov_b32_e32 v94, v0
	v_mov_b32_e32 v95, v0
	v_mov_b32_e32 v100, v0
	v_mov_b32_e32 v101, v0
	v_mov_b32_e32 v102, v0
	v_mov_b32_e32 v103, v0
	v_mov_b32_e32 v104, v0
	v_mov_b32_e32 v105, v0
	v_mov_b32_e32 v106, v0
	v_mov_b32_e32 v107, v0
	v_and_b32_e32 v224, 3, v172
	v_lshrrev_b32_e32 v225, 4, v172
	v_bitop3_b32 v224, v225, v224, 2 bitop3:0x6c
	v_ashrrev_i32_e32 v225, 6, v172
	v_bfe_u32 v222, v172, 2, 4
	v_readfirstlane_b32 s32, v225
	v_lshl_or_b32 v222, v225, 4, v222
	v_lshlrev_b32_e32 v222, 11, v222
	v_lshl_or_b32 v222, v224, 4, v222
	v_mov_b32_e32 v223, 0
	s_lshl_b32 s32, s32, 10
	v_lshl_add_u64 v[208:209], s[30:31], 0, v[222:223]
	s_mov_b64 s[98:99], 0x1b100080
	v_lshl_add_u64 v[208:209], v[208:209], 0, s[98:99]
	v_lshl_add_u64 v[210:211], s[30:31], 0, v[222:223]
	s_mov_b64 s[98:99], 0x1b120080
	v_lshl_add_u64 v[210:211], v[210:211], 0, s[98:99]
	v_lshl_add_u64 v[212:213], s[30:31], 0, v[222:223]
	s_mov_b64 s[98:99], 0x1b140080
	v_lshl_add_u64 v[212:213], v[212:213], 0, s[98:99]
	v_lshl_add_u64 v[214:215], s[30:31], 0, v[222:223]
	s_mov_b64 s[98:99], 0x1b160080
	v_lshl_add_u64 v[214:215], v[214:215], 0, s[98:99]
	v_lshl_add_u64 v[218:219], s[34:35], 0, v[222:223]
	s_mov_b64 s[98:99], 0x1bd00080
	v_lshl_add_u64 v[218:219], v[218:219], 0, s[98:99]
	v_lshl_add_u64 v[220:221], s[34:35], 0, v[222:223]
	s_mov_b64 s[98:99], 0x1bd20080
	v_lshl_add_u64 v[220:221], v[220:221], 0, s[98:99]
.LBB0_821:
	s_waitcnt vmcnt(6)
	s_waitcnt lgkmcnt(0)
	s_barrier
	s_mul_i32 s26, s72, 0x6000
	s_add_i32 s33, s26, 0xffffa000
	s_cmp_gt_i32 s72, 0
	s_cselect_b32 s33, s33, 0xc000
	s_add_i32 s33, s33, s32
	v_add_u32_e32 v131, s26, v129
	v_add_u32_e32 v139, v131, v128
	v_add_u32_e32 v131, v131, v130
	ds_read_b128 v[132:135], v139 offset:16384
	ds_read_b128 v[140:143], v139 offset:17408
	ds_read_b128 v[144:147], v139 offset:18432
	ds_read_b128 v[148:151], v139 offset:19456
	ds_read_b128 v[152:155], v131
	ds_read_b128 v[156:159], v131 offset:1024
	ds_read_b128 v[160:163], v131 offset:2048
	ds_read_b128 v[164:167], v131 offset:3072
	ds_read_b128 v[192:195], v131 offset:4096
	ds_read_b128 v[196:199], v131 offset:5120
	ds_read_b128 v[200:203], v131 offset:6144
	ds_read_b128 v[204:207], v131 offset:7168
	s_mov_b32 m0, s33
	s_nop 0
	global_load_lds_dwordx4 v[208:209], off
	v_lshl_add_u64 v[208:209], v[208:209], 0, 64
	s_add_i32 m0, s33, 0x1000
	s_setprio 1
	s_waitcnt lgkmcnt(7)
	v_mfma_f32_16x16x32_bf16 v[124:127], v[132:135], v[152:155], v[124:127]
	v_mfma_f32_16x16x32_bf16 v[120:123], v[140:143], v[152:155], v[120:123]
	v_mfma_f32_16x16x32_bf16 v[116:119], v[144:147], v[152:155], v[116:119]
	v_mfma_f32_16x16x32_bf16 v[112:115], v[148:151], v[152:155], v[112:115]
	global_load_lds_dwordx4 v[210:211], off
	v_lshl_add_u64 v[210:211], v[210:211], 0, 64
	s_add_i32 m0, s33, 0x2000
	s_waitcnt lgkmcnt(6)
	v_mfma_f32_16x16x32_bf16 v[108:111], v[132:135], v[156:159], v[108:111]
	v_mfma_f32_16x16x32_bf16 v[96:99], v[140:143], v[156:159], v[96:99]
	v_mfma_f32_16x16x32_bf16 v[84:87], v[144:147], v[156:159], v[84:87]
	v_mfma_f32_16x16x32_bf16 v[80:83], v[148:151], v[156:159], v[80:83]
	global_load_lds_dwordx4 v[212:213], off
	v_lshl_add_u64 v[212:213], v[212:213], 0, 64
	s_add_i32 m0, s33, 0x3000
	s_waitcnt lgkmcnt(5)
	v_mfma_f32_16x16x32_bf16 v[76:79], v[132:135], v[160:163], v[76:79]
	v_mfma_f32_16x16x32_bf16 v[72:75], v[140:143], v[160:163], v[72:75]
	v_mfma_f32_16x16x32_bf16 v[68:71], v[144:147], v[160:163], v[68:71]
	v_mfma_f32_16x16x32_bf16 v[64:67], v[148:151], v[160:163], v[64:67]
	global_load_lds_dwordx4 v[214:215], off
	v_lshl_add_u64 v[214:215], v[214:215], 0, 64
	s_add_i32 m0, s33, 0x4000
	s_waitcnt lgkmcnt(4)
	v_mfma_f32_16x16x32_bf16 v[60:63], v[132:135], v[164:167], v[60:63]
	v_mfma_f32_16x16x32_bf16 v[56:59], v[140:143], v[164:167], v[56:59]
	v_mfma_f32_16x16x32_bf16 v[52:55], v[144:147], v[164:167], v[52:55]
	v_mfma_f32_16x16x32_bf16 v[48:51], v[148:151], v[164:167], v[48:51]
	global_load_lds_dwordx4 v[218:219], off
	v_lshl_add_u64 v[218:219], v[218:219], 0, 64
	s_add_i32 m0, s33, 0x5000
	s_waitcnt lgkmcnt(3)
	v_mfma_f32_16x16x32_bf16 v[44:47], v[132:135], v[192:195], v[44:47]
	v_mfma_f32_16x16x32_bf16 v[40:43], v[140:143], v[192:195], v[40:43]
	v_mfma_f32_16x16x32_bf16 v[36:39], v[144:147], v[192:195], v[36:39]
	v_mfma_f32_16x16x32_bf16 v[32:35], v[148:151], v[192:195], v[32:35]
	global_load_lds_dwordx4 v[220:221], off
	v_lshl_add_u64 v[220:221], v[220:221], 0, 64
	s_waitcnt lgkmcnt(2)
	v_mfma_f32_16x16x32_bf16 v[28:31], v[132:135], v[196:199], v[28:31]
	v_mfma_f32_16x16x32_bf16 v[24:27], v[140:143], v[196:199], v[24:27]
	v_mfma_f32_16x16x32_bf16 v[20:23], v[144:147], v[196:199], v[20:23]
	v_mfma_f32_16x16x32_bf16 v[16:19], v[148:151], v[196:199], v[16:19]
	s_waitcnt lgkmcnt(1)
	v_mfma_f32_16x16x32_bf16 v[12:15], v[132:135], v[200:203], v[12:15]
	v_mfma_f32_16x16x32_bf16 v[8:11], v[140:143], v[200:203], v[8:11]
	v_mfma_f32_16x16x32_bf16 v[4:7], v[144:147], v[200:203], v[4:7]
	v_mfma_f32_16x16x32_bf16 v[0:3], v[148:151], v[200:203], v[0:3]
	s_waitcnt lgkmcnt(0)
	v_mfma_f32_16x16x32_bf16 v[88:91], v[132:135], v[204:207], v[88:91]
	v_mfma_f32_16x16x32_bf16 v[92:95], v[140:143], v[204:207], v[92:95]
	v_mfma_f32_16x16x32_bf16 v[100:103], v[144:147], v[204:207], v[100:103]
	v_mfma_f32_16x16x32_bf16 v[104:107], v[148:151], v[204:207], v[104:107]
	s_setprio 0
	s_add_i32 s26, s72, 1
	s_cmp_lg_u32 s72, 2
	s_cselect_b32 s72, s26, 0
	s_add_u32 s36, s36, 64
	s_addc_u32 s37, s37, 0
	s_cmpk_eq_i32 s36, 0x780
	s_cbranch_scc0 .LBB0_821
; template <bool TRANS, class Epi>
; DEVI int g2_body(const G2Tile& t, int st, char* smem, bool has_next, const G2Tile& nxt, const Epi& epi) {
;     ...
;     for (int kt = 0; kt < nk; ++kt) {
;         if (kt + 1 < nk) asm volatile("s_waitcnt vmcnt(6)" ::: "memory");
;         else asm volatile("s_waitcnt vmcnt(0)" ::: "memory");
;         __syncthreads();
;         if (kt + 2 < nk) g2_issue(t, kt + 2, st >= 1 ? st - 1 : 2, smem);
;         const char* sa = smem + st * 24576 + frag;
;         bf16x8 bfr[4];
; #pragma unroll
;         for (int n = 0; n < 4; ++n) bfr[n] = *(const bf16x8*)(sa + (16 + wc * 4 + n) * 1024);
; #pragma unroll
;         for (int mh = 0; mh < 2; ++mh) {
;             bf16x8 af[4];
; #pragma unroll
;             for (int m = 0; m < 4; ++m) af[m] = *(const bf16x8*)(sa + (wr * 8 + mh * 4 + m) * 1024);
;             __builtin_amdgcn_s_setprio(1);
; #pragma unroll
;             for (int m = 0; m < 4; ++m)
; #pragma unroll
;                 for (int n = 0; n < 4; ++n)
;                     acc[mh * 4 + m][n] = TRANS ? __builtin_amdgcn_mfma_f32_16x16x32_bf16(bfr[n], af[m], acc[mh * 4 + m][n], 0, 0, 0)
;                                                : __builtin_amdgcn_mfma_f32_16x16x32_bf16(af[m], bfr[n], acc[mh * 4 + m][n], 0, 0, 0);
;             __builtin_amdgcn_s_setprio(0);
;         }
;         st = st == 2 ? 0 : st + 1;
;     }
;     if (has_next) g2_prologue(nxt, st, smem);
	s_mul_i32 s26, s72, 0x6000
	v_add_u32_e32 v131, s26, v129
	v_add_u32_e32 v139, v131, v128
	v_add_u32_e32 v131, v131, v130
	s_waitcnt vmcnt(6)
	s_waitcnt vmcnt(0)
	s_barrier
	ds_read_b128 v[132:135], v139 offset:16384
	ds_read_b128 v[140:143], v139 offset:17408
	ds_read_b128 v[144:147], v139 offset:18432
	ds_read_b128 v[148:151], v139 offset:19456
	ds_read_b128 v[152:155], v131
	ds_read_b128 v[156:159], v131 offset:1024
	ds_read_b128 v[160:163], v131 offset:2048
	ds_read_b128 v[164:167], v131 offset:3072
	s_setprio 1
	s_waitcnt lgkmcnt(3)
	v_mfma_f32_16x16x32_bf16 v[116:119], v[144:147], v[152:155], v[116:119]
	s_waitcnt lgkmcnt(2)
	v_mfma_f32_16x16x32_bf16 v[108:111], v[132:135], v[156:159], v[108:111]
	v_mfma_f32_16x16x32_bf16 v[96:99], v[140:143], v[156:159], v[96:99]
	v_mfma_f32_16x16x32_bf16 v[84:87], v[144:147], v[156:159], v[84:87]
	v_mfma_f32_16x16x32_bf16 v[80:83], v[148:151], v[156:159], v[80:83]
	s_waitcnt lgkmcnt(1)
	v_mfma_f32_16x16x32_bf16 v[76:79], v[132:135], v[160:163], v[76:79]
	v_mfma_f32_16x16x32_bf16 v[72:75], v[140:143], v[160:163], v[72:75]
	v_mfma_f32_16x16x32_bf16 v[68:71], v[144:147], v[160:163], v[68:71]
	v_mfma_f32_16x16x32_bf16 v[64:67], v[148:151], v[160:163], v[64:67]
	s_waitcnt lgkmcnt(0)
	v_mfma_f32_16x16x32_bf16 v[60:63], v[132:135], v[164:167], v[60:63]
	v_mfma_f32_16x16x32_bf16 v[56:59], v[140:143], v[164:167], v[56:59]
	v_mfma_f32_16x16x32_bf16 v[52:55], v[144:147], v[164:167], v[52:55]
	v_mfma_f32_16x16x32_bf16 v[48:51], v[148:151], v[164:167], v[48:51]
	v_mfma_f32_16x16x32_bf16 v[124:127], v[132:135], v[152:155], v[124:127]
	v_mfma_f32_16x16x32_bf16 v[120:123], v[140:143], v[152:155], v[120:123]
	v_mfma_f32_16x16x32_bf16 v[112:115], v[148:151], v[152:155], v[112:115]
	s_setprio 0
	ds_read_b128 v[152:155], v131 offset:4096
	ds_read_b128 v[156:159], v131 offset:5120
	ds_read_b128 v[160:163], v131 offset:6144
	ds_read_b128 v[164:167], v131 offset:7168
	s_setprio 1
	s_waitcnt lgkmcnt(3)
	v_mfma_f32_16x16x32_bf16 v[44:47], v[132:135], v[152:155], v[44:47]
	v_mfma_f32_16x16x32_bf16 v[40:43], v[140:143], v[152:155], v[40:43]
	v_mfma_f32_16x16x32_bf16 v[36:39], v[144:147], v[152:155], v[36:39]
	v_mfma_f32_16x16x32_bf16 v[32:35], v[148:151], v[152:155], v[32:35]
	s_waitcnt lgkmcnt(2)
	v_mfma_f32_16x16x32_bf16 v[28:31], v[132:135], v[156:159], v[28:31]
	v_mfma_f32_16x16x32_bf16 v[24:27], v[140:143], v[156:159], v[24:27]
	v_mfma_f32_16x16x32_bf16 v[20:23], v[144:147], v[156:159], v[20:23]
	v_mfma_f32_16x16x32_bf16 v[16:19], v[148:151], v[156:159], v[16:19]
	s_waitcnt lgkmcnt(1)
	v_mfma_f32_16x16x32_bf16 v[12:15], v[132:135], v[160:163], v[12:15]
	v_mfma_f32_16x16x32_bf16 v[8:11], v[140:143], v[160:163], v[8:11]
	v_mfma_f32_16x16x32_bf16 v[4:7], v[144:147], v[160:163], v[4:7]
	v_mfma_f32_16x16x32_bf16 v[0:3], v[148:151], v[160:163], v[0:3]
	s_waitcnt lgkmcnt(0)
	v_mfma_f32_16x16x32_bf16 v[152:155], v[132:135], v[164:167], v[88:91]
	v_mfma_f32_16x16x32_bf16 v[140:143], v[140:143], v[164:167], v[92:95]
	v_mfma_f32_16x16x32_bf16 v[156:159], v[144:147], v[164:167], v[100:103]
	v_mfma_f32_16x16x32_bf16 v[104:107], v[148:151], v[164:167], v[104:107]
	s_setprio 0
	s_add_i32 s26, s72, 1
	s_cmp_lg_u32 s72, 2
	s_cselect_b32 s26, s26, 0
	s_mul_i32 s30, s26, 0x6000
	v_add_u32_e32 v100, s30, v129
	v_add_u32_e32 v139, v100, v130
	v_add_u32_e32 v100, v100, v128
	s_waitcnt vmcnt(0)
	s_barrier
	ds_read_b128 v[160:163], v139 offset:3072
	ds_read_b128 v[164:167], v139 offset:2048
	ds_read_b128 v[88:91], v139 offset:1024
	ds_read_b128 v[92:95], v139
	ds_read_b128 v[168:171], v100 offset:19456
	ds_read_b128 v[186:189], v100 offset:18432
	ds_read_b128 v[190:193], v100 offset:17408
	ds_read_b128 v[194:197], v100 offset:16384
	s_setprio 1
	s_waitcnt lgkmcnt(0)
	v_mfma_f32_16x16x32_bf16 v[148:151], v[194:197], v[92:95], v[124:127]
	v_mfma_f32_16x16x32_bf16 v[144:147], v[190:193], v[92:95], v[120:123]
	v_mfma_f32_16x16x32_bf16 v[132:135], v[186:189], v[92:95], v[116:119]
	v_mfma_f32_16x16x32_bf16 v[128:131], v[168:171], v[92:95], v[112:115]
	v_mfma_f32_16x16x32_bf16 v[116:119], v[194:197], v[88:91], v[108:111]
	v_mfma_f32_16x16x32_bf16 v[108:111], v[190:193], v[88:91], v[96:99]
	v_mfma_f32_16x16x32_bf16 v[100:103], v[186:189], v[88:91], v[84:87]
	v_mfma_f32_16x16x32_bf16 v[96:99], v[168:171], v[88:91], v[80:83]
	v_mfma_f32_16x16x32_bf16 v[92:95], v[194:197], v[164:167], v[76:79]
	v_mfma_f32_16x16x32_bf16 v[88:91], v[190:193], v[164:167], v[72:75]
	v_mfma_f32_16x16x32_bf16 v[84:87], v[186:189], v[164:167], v[68:71]
	v_mfma_f32_16x16x32_bf16 v[80:83], v[168:171], v[164:167], v[64:67]
	v_mfma_f32_16x16x32_bf16 v[76:79], v[194:197], v[160:163], v[60:63]
	v_mfma_f32_16x16x32_bf16 v[72:75], v[190:193], v[160:163], v[56:59]
	v_mfma_f32_16x16x32_bf16 v[68:71], v[186:189], v[160:163], v[52:55]
	v_mfma_f32_16x16x32_bf16 v[64:67], v[168:171], v[160:163], v[48:51]
	s_setprio 0
	s_nop 1
	ds_read_b128 v[48:51], v139 offset:4096
	ds_read_b128 v[112:115], v139 offset:5120
	ds_read_b128 v[120:123], v139 offset:6144
	ds_read_b128 v[124:127], v139 offset:7168
	s_setprio 1
	s_waitcnt lgkmcnt(3)
	v_mfma_f32_16x16x32_bf16 v[60:63], v[194:197], v[48:51], v[44:47]
	v_mfma_f32_16x16x32_bf16 v[56:59], v[190:193], v[48:51], v[40:43]
	v_mfma_f32_16x16x32_bf16 v[52:55], v[186:189], v[48:51], v[36:39]
	v_mfma_f32_16x16x32_bf16 v[48:51], v[168:171], v[48:51], v[32:35]
	s_waitcnt lgkmcnt(2)
	v_mfma_f32_16x16x32_bf16 v[44:47], v[194:197], v[112:115], v[28:31]
	v_mfma_f32_16x16x32_bf16 v[40:43], v[190:193], v[112:115], v[24:27]
	v_mfma_f32_16x16x32_bf16 v[36:39], v[186:189], v[112:115], v[20:23]
	v_mfma_f32_16x16x32_bf16 v[32:35], v[168:171], v[112:115], v[16:19]
	s_waitcnt lgkmcnt(1)
	v_mfma_f32_16x16x32_bf16 v[28:31], v[194:197], v[120:123], v[12:15]
	v_mfma_f32_16x16x32_bf16 v[24:27], v[190:193], v[120:123], v[8:11]
	v_mfma_f32_16x16x32_bf16 v[20:23], v[186:189], v[120:123], v[4:7]
	v_mfma_f32_16x16x32_bf16 v[16:19], v[168:171], v[120:123], v[0:3]
	s_waitcnt lgkmcnt(0)
	v_mfma_f32_16x16x32_bf16 v[12:15], v[194:197], v[124:127], v[152:155]
	v_mfma_f32_16x16x32_bf16 v[8:11], v[190:193], v[124:127], v[140:143]
	v_mfma_f32_16x16x32_bf16 v[4:7], v[186:189], v[124:127], v[156:159]
	v_mfma_f32_16x16x32_bf16 v[0:3], v[168:171], v[124:127], v[104:107]
	s_setprio 0
	s_add_i32 s30, s26, 1
	s_cmp_lg_u32 s26, 2
	s_cselect_b32 s72, s30, 0
	s_and_b64 vcc, exec, s[0:1]
	s_cbranch_vccz .LBB0_824
; DEVI int opaque_tid() { int t = (int)threadIdx.x; asm volatile("" : "+v"(t)); return t; }
; DEVI void g2_issue(const G2Tile& t, int kt, int st, char* smem) {
;     const int tid = opaque_tid(), lane = tid & 63, w = tid >> 6;
;     const int rr = lane >> 2, sch = (lane & 3) ^ ((lane >> 5) << 1);
;     const bf16_t* ap = t.A + (size_t)kt * 32 + (size_t)(w * 16 + rr) * t.lda + sch * 8;
;     const bf16_t* bp = t.Bt + (size_t)kt * 32 + (size_t)(w * 16 + rr) * t.ldb + sch * 8;
;     char* sa = smem + st * 24576 + w * 1024 + lane * 16;
; #pragma unroll
;     for (int i = 0; i < 4; ++i) __builtin_amdgcn_global_load_lds((const unsigned*)(ap + (size_t)(64 * i) * t.lda), (unsigned*)(sa + i * 4096), 16, 0, 0);
; #pragma unroll
;     for (int i = 0; i < 2; ++i) __builtin_amdgcn_global_load_lds((const unsigned*)(bp + (size_t)(64 * i) * t.ldb), (unsigned*)(sa + 16384 + i * 4096), 16, 0, 0);
; }
; DEVI void g2_prologue(const G2Tile& t, int st, char* smem) {
;     g2_issue(t, 0, st, smem);
;     g2_issue(t, 1, st == 2 ? 0 : st + 1, smem);
	v_mov_b32_e32 v104, v172
	s_mul_i32 s0, s72, 0x6000
	v_and_b32_e32 v112, 63, v104
	v_ashrrev_i32_e32 v113, 6, v104
	v_bfe_u32 v105, v104, 2, 4
	v_and_b32_e32 v106, 3, v104
	v_lshrrev_b32_e32 v104, 4, v104
	v_bitop3_b32 v114, v104, v106, 2 bitop3:0x6c
	v_lshl_or_b32 v104, v113, 4, v105
	v_ashrrev_i32_e32 v105, 31, v104
	s_add_i32 s1, s0, 0
	v_lshlrev_b32_e32 v113, 10, v113
	v_lshlrev_b32_e32 v112, 4, v112
	v_lshlrev_b64 v[104:105], 11, v[104:105]
	v_lshlrev_b32_e32 v184, 4, v114
	v_add3_u32 v114, s1, v113, v112
	v_lshl_add_u64 v[106:107], s[20:21], 0, v[104:105]
	v_readfirstlane_b32 s1, v114
	v_add_u32_e32 v115, 0x1000, v114
	v_lshl_add_u64 v[106:107], v[106:107], 0, v[184:185]
	s_mov_b32 m0, s1
	v_readfirstlane_b32 s1, v115
	v_add_u32_e32 v115, 0x2000, v114
	global_load_lds_dwordx4 v[106:107], off
	v_lshl_add_u64 v[112:113], v[106:107], 0, s[6:7]
	s_mov_b32 m0, s1
	v_readfirstlane_b32 s1, v115
	global_load_lds_dwordx4 v[112:113], off
	v_lshl_add_u64 v[112:113], v[106:107], 0, s[8:9]
	s_mov_b32 m0, s1
	v_lshl_add_u64 v[106:107], v[106:107], 0, s[10:11]
	global_load_lds_dwordx4 v[112:113], off
	v_add_u32_e32 v112, 0x3000, v114
	v_lshl_add_u64 v[104:105], s[22:23], 0, v[104:105]
	v_readfirstlane_b32 s1, v112
	s_mov_b32 m0, s1
	v_lshl_add_u64 v[104:105], v[104:105], 0, v[184:185]
	global_load_lds_dwordx4 v[106:107], off
	v_add_u32_e32 v106, 0x4000, v114
	s_addk_i32 s0, 0x6000
	v_readfirstlane_b32 s1, v106
	v_add_u32_e32 v106, 0x5000, v114
	s_mov_b32 m0, s1
	v_readfirstlane_b32 s1, v106
	global_load_lds_dwordx4 v[104:105], off
	v_lshl_add_u64 v[104:105], v[104:105], 0, s[6:7]
	s_mov_b32 m0, s1
	s_cmp_lg_u32 s72, 2
	global_load_lds_dwordx4 v[104:105], off
	v_mov_b32_e32 v104, v172
	s_cselect_b32 s0, s0, 0
	v_and_b32_e32 v114, 63, v104
	v_ashrrev_i32_e32 v115, 6, v104
	v_bfe_u32 v105, v104, 2, 4
	v_and_b32_e32 v106, 3, v104
	v_lshrrev_b32_e32 v104, 4, v104
	v_bitop3_b32 v112, v104, v106, 2 bitop3:0x6c
	v_lshl_or_b32 v104, v115, 4, v105
	v_ashrrev_i32_e32 v105, 31, v104
	v_lshlrev_b64 v[104:105], 11, v[104:105]
	s_add_i32 s0, s0, 0
	v_lshlrev_b32_e32 v115, 10, v115
	v_lshlrev_b32_e32 v114, 4, v114
	v_lshl_add_u64 v[106:107], s[20:21], 0, v[104:105]
	v_lshlrev_b32_e32 v184, 4, v112
	v_add3_u32 v114, s0, v115, v114
	v_lshl_add_u64 v[106:107], v[106:107], 0, v[184:185]
	v_readfirstlane_b32 s0, v114
	v_add_u32_e32 v115, 0x1000, v114
	v_lshl_add_u64 v[112:113], v[106:107], 0, 64
	s_mov_b32 m0, s0
	v_readfirstlane_b32 s0, v115
	v_add_u32_e32 v115, 0x2000, v114
	global_load_lds_dwordx4 v[112:113], off
	v_lshl_add_u64 v[112:113], v[106:107], 0, s[12:13]
	s_mov_b32 m0, s0
	v_readfirstlane_b32 s0, v115
	global_load_lds_dwordx4 v[112:113], off
	v_lshl_add_u64 v[112:113], v[106:107], 0, s[14:15]
	s_mov_b32 m0, s0
	v_lshl_add_u64 v[104:105], s[22:23], 0, v[104:105]
	global_load_lds_dwordx4 v[112:113], off
	v_add_u32_e32 v112, 0x3000, v114
	v_lshl_add_u64 v[106:107], v[106:107], 0, s[16:17]
	v_readfirstlane_b32 s0, v112
	v_add_u32_e32 v112, 0x4000, v114
	s_mov_b32 m0, s0
	v_lshl_add_u64 v[104:105], v[104:105], 0, v[184:185]
	v_readfirstlane_b32 s0, v112
	global_load_lds_dwordx4 v[106:107], off
	v_lshl_add_u64 v[106:107], v[104:105], 0, 64
	s_mov_b32 m0, s0
	v_lshl_add_u64 v[104:105], v[104:105], 0, s[12:13]
	global_load_lds_dwordx4 v[106:107], off
	v_add_u32_e32 v106, 0x5000, v114
	s_nop 0
	v_readfirstlane_b32 s0, v106
	s_mov_b32 m0, s0
	s_nop 0
	global_load_lds_dwordx4 v[104:105], off
